# GEMM K-loops: the s_setprio 0/1 flip between the two MFMA blocks of each super-phase removed (priority stays raised through the whole 32-MFMA segment)
# speedup vs baseline: 1.0044x; 1.0044x over previous
; #define PG8_STAGE(bufoff, gbase, voff) do { _Pragma("unroll") for (int _i = 0; _i < 2; ++_i) \
;         __builtin_amdgcn_global_load_lds((const unsigned*)((const char*)(gbase) + (voff)[_i]), (PG8_LAS unsigned*)(lds + (bufoff) + ldsw + _i * 8192), 16, 0, 0); } while (0)
; #define PG8_LDA(dst, b, h) do { _Pragma("unroll") for (int m = 0; m < 4; ++m) _Pragma("unroll") for (int k = 0; k < 2; ++k) dst[m][k] = *(const PG8_LAS bf16x8*)(lds + PG8_SA(b, h) + aoff + m * 2048 + k * 1024); } while (0)
; #define PG8_LDB(dst, b, h) do { _Pragma("unroll") for (int n = 0; n < 2; ++n) _Pragma("unroll") for (int k = 0; k < 2; ++k) dst[n][k] = *(const PG8_LAS bf16x8*)(lds + PG8_SB(b, h) + boff + n * 2048 + k * 1024); } while (0)
; #define PG8_MMA(ai, bj, At, Bt) do { __builtin_amdgcn_s_setprio(1); _Pragma("unroll") for (int m = 0; m < 4; ++m) _Pragma("unroll") for (int n = 0; n < 2; ++n) _Pragma("unroll") for (int k = 0; k < 2; ++k) \
;         acc[ai][bj][m][n] = __builtin_amdgcn_mfma_f32_16x16x32_bf16(Bt[n][k], At[m][k], acc[ai][bj][m][n], 0, 0, 0); __builtin_amdgcn_s_setprio(0); } while (0)
; #define PG8_WAIT_V(n) asm volatile("s_waitcnt vmcnt(" #n ")" ::: "memory")
; #define PG8_WAIT_L(n) asm volatile("s_waitcnt lgkmcnt(" #n ")" ::: "memory")
; #define PG8_BAR __builtin_amdgcn_s_barrier()
; #define PG8_SCHED __builtin_amdgcn_sched_barrier(0)
; template <class Epi, class Sched, bool ALIGN_EPI = false, bool SP2 = false>
; __device__ __forceinline__ void gemm_phase(PG8_LAS unsigned char* lds, const Gemm g, const Sched& S, const Epi& E, const int tid) {
;     ...
;             PG8_LDB(B0, 0, 0); PG8_LDB(B1, 0, 1); PG8_SCHED; PG8_LDA(At, 0, 0); PG8_STAGE(PG8_SA(1, 1), a1 + hstep, voffA);
;             PG8_WAIT_V(8); PG8_WAIT_L(0); PG8_BAR; PG8_MMA(0, 0, At, B0); PG8_MMA(0, 1, At, B1); PG8_BAR; PG8_SCHED;
;             PG8_LDA(At, 0, 1); PG8_STAGE(PG8_SB(0, 0), b2, voffB); PG8_STAGE(PG8_SB(0, 1), b2 + hstep, voffB); PG8_STAGE(PG8_SA(0, 0), a2, voffA);
;             PG8_WAIT_V(8); PG8_WAIT_L(0); PG8_BAR; PG8_MMA(1, 0, At, B0); PG8_MMA(1, 1, At, B1); PG8_BAR; PG8_SCHED;
.LBB0_144:
	s_add_i32 vcc_lo, s66, 2
	s_add_u32 s10, s0, 0x80
	s_addc_u32 s11, s1, 0
	s_add_i32 s12, 0, 0x10000
	s_cmp_eq_u32 s92, s66
	s_cselect_b32 s67, s43, s11
	s_cselect_b32 s66, s42, s10
	v_add_u32_e32 v143, s12, v140
	s_cselect_b32 s11, s65, s9
	s_cselect_b32 s10, s64, s8
	s_add_i32 s13, 0, 0x14000
	ds_read_b128 v[144:147], v143
	ds_read_b128 v[148:151], v143 offset:1024
	ds_read_b128 v[152:155], v143 offset:2048
	ds_read_b128 v[156:159], v143 offset:3072
	v_add_u32_e32 v143, s13, v140
	ds_read_b128 v[160:163], v143
	ds_read_b128 v[164:167], v143 offset:1024
	ds_read_b128 v[168:171], v143 offset:2048
	ds_read_b128 v[172:175], v143 offset:3072
	v_lshl_add_u64 v[212:213], s[0:1], 0, v[134:135]
	s_add_i32 m0, s77, 0xc000
	ds_read_b128 v[176:179], v142
	ds_read_b128 v[180:183], v142 offset:1024
	ds_read_b128 v[184:187], v142 offset:2048
	ds_read_b128 v[188:191], v142 offset:3072
	ds_read_b128 v[196:199], v142 offset:4096
	ds_read_b128 v[200:203], v142 offset:5120
	ds_read_b128 v[204:207], v142 offset:6144
	ds_read_b128 v[208:211], v142 offset:7168
	global_load_lds_dwordx4 v[212:213], off
	v_lshl_add_u64 v[212:213], s[0:1], 0, v[136:137]
	s_add_i32 m0, s77, 0xe000
	s_nop 0
	global_load_lds_dwordx4 v[212:213], off
	s_waitcnt vmcnt(8)
	s_waitcnt lgkmcnt(0)
	s_barrier
	s_setprio 1
	s_waitcnt lgkmcnt(0)
	v_mfma_f32_16x16x32_bf16 v[120:123], v[144:147], v[176:179], v[120:123]
	v_mfma_f32_16x16x32_bf16 v[124:127], v[152:155], v[176:179], v[124:127]
	v_mfma_f32_16x16x32_bf16 v[108:111], v[144:147], v[184:187], v[108:111]
	v_mfma_f32_16x16x32_bf16 v[104:107], v[152:155], v[184:187], v[104:107]
	v_mfma_f32_16x16x32_bf16 v[92:95], v[144:147], v[196:199], v[92:95]
	v_mfma_f32_16x16x32_bf16 v[88:91], v[152:155], v[196:199], v[88:91]
	v_mfma_f32_16x16x32_bf16 v[76:79], v[144:147], v[204:207], v[76:79]
	v_mfma_f32_16x16x32_bf16 v[72:75], v[152:155], v[204:207], v[72:75]
	v_mfma_f32_16x16x32_bf16 v[120:123], v[148:151], v[180:183], v[120:123]
	v_mfma_f32_16x16x32_bf16 v[124:127], v[156:159], v[180:183], v[124:127]
	v_mfma_f32_16x16x32_bf16 v[108:111], v[148:151], v[188:191], v[108:111]
	v_mfma_f32_16x16x32_bf16 v[104:107], v[156:159], v[188:191], v[104:107]
	v_mfma_f32_16x16x32_bf16 v[92:95], v[148:151], v[200:203], v[92:95]
	v_mfma_f32_16x16x32_bf16 v[88:91], v[156:159], v[200:203], v[88:91]
	v_mfma_f32_16x16x32_bf16 v[76:79], v[148:151], v[208:211], v[76:79]
	v_mfma_f32_16x16x32_bf16 v[72:75], v[156:159], v[208:211], v[72:75]
	v_mfma_f32_16x16x32_bf16 v[116:119], v[160:163], v[176:179], v[116:119]
	v_mfma_f32_16x16x32_bf16 v[112:115], v[168:171], v[176:179], v[112:115]
	v_mfma_f32_16x16x32_bf16 v[100:103], v[160:163], v[184:187], v[100:103]
	v_mfma_f32_16x16x32_bf16 v[96:99], v[168:171], v[184:187], v[96:99]
	v_mfma_f32_16x16x32_bf16 v[84:87], v[160:163], v[196:199], v[84:87]
	v_mfma_f32_16x16x32_bf16 v[80:83], v[168:171], v[196:199], v[80:83]
	v_mfma_f32_16x16x32_bf16 v[68:71], v[160:163], v[204:207], v[68:71]
	v_mfma_f32_16x16x32_bf16 v[64:67], v[168:171], v[204:207], v[64:67]
	v_mfma_f32_16x16x32_bf16 v[116:119], v[164:167], v[180:183], v[116:119]
	v_mfma_f32_16x16x32_bf16 v[112:115], v[172:175], v[180:183], v[112:115]
	v_mfma_f32_16x16x32_bf16 v[100:103], v[164:167], v[188:191], v[100:103]
	v_mfma_f32_16x16x32_bf16 v[96:99], v[172:175], v[188:191], v[96:99]
	v_mfma_f32_16x16x32_bf16 v[84:87], v[164:167], v[200:203], v[84:87]
	v_mfma_f32_16x16x32_bf16 v[80:83], v[172:175], v[200:203], v[80:83]
	v_mfma_f32_16x16x32_bf16 v[68:71], v[164:167], v[208:211], v[68:71]
	v_mfma_f32_16x16x32_bf16 v[64:67], v[172:175], v[208:211], v[64:67]
	s_setprio 0
	s_barrier
	s_add_i32 s12, s12, s4
	v_lshl_add_u64 v[212:213], s[10:11], 0, v[192:193]
	s_mov_b32 m0, s12
	ds_read_b128 v[176:179], v142 offset:16384
	ds_read_b128 v[180:183], v142 offset:17408
	ds_read_b128 v[184:187], v142 offset:18432
	ds_read_b128 v[188:191], v142 offset:19456
	ds_read_b128 v[196:199], v142 offset:20480
	ds_read_b128 v[200:203], v142 offset:21504
	ds_read_b128 v[204:207], v142 offset:22528
	ds_read_b128 v[208:211], v142 offset:23552
	global_load_lds_dwordx4 v[212:213], off
	s_add_i32 m0, s12, 0x2000
	v_lshl_add_u64 v[214:215], s[10:11], 0, v[128:129]
	s_add_u32 s10, s10, s30
	s_addc_u32 s11, s11, s31
	s_add_i32 s12, s13, s4
	global_load_lds_dwordx4 v[214:215], off
	v_lshl_add_u64 v[216:217], s[10:11], 0, v[192:193]
	s_mov_b32 m0, s12
	v_lshl_add_u64 v[218:219], s[10:11], 0, v[128:129]
	global_load_lds_dwordx4 v[216:217], off
	s_add_i32 m0, s12, 0x2000
	v_lshl_add_u64 v[220:221], s[66:67], 0, v[132:133]
	global_load_lds_dwordx4 v[218:219], off
	s_mov_b32 m0, s77
	v_lshl_add_u64 v[222:223], s[66:67], 0, v[130:131]
	global_load_lds_dwordx4 v[220:221], off
	s_mov_b32 m0, s82
	s_nop 0
	global_load_lds_dwordx4 v[222:223], off
	s_waitcnt vmcnt(8)
	s_waitcnt lgkmcnt(0)
	s_barrier
; #define PG8_STAGE(bufoff, gbase, voff) do { _Pragma("unroll") for (int _i = 0; _i < 2; ++_i) \
;         __builtin_amdgcn_global_load_lds((const unsigned*)((const char*)(gbase) + (voff)[_i]), (PG8_LAS unsigned*)(lds + (bufoff) + ldsw + _i * 8192), 16, 0, 0); } while (0)
; #define PG8_LDA(dst, b, h) do { _Pragma("unroll") for (int m = 0; m < 4; ++m) _Pragma("unroll") for (int k = 0; k < 2; ++k) dst[m][k] = *(const PG8_LAS bf16x8*)(lds + PG8_SA(b, h) + aoff + m * 2048 + k * 1024); } while (0)
; #define PG8_LDB(dst, b, h) do { _Pragma("unroll") for (int n = 0; n < 2; ++n) _Pragma("unroll") for (int k = 0; k < 2; ++k) dst[n][k] = *(const PG8_LAS bf16x8*)(lds + PG8_SB(b, h) + boff + n * 2048 + k * 1024); } while (0)
; #define PG8_MMA(ai, bj, At, Bt) do { __builtin_amdgcn_s_setprio(1); _Pragma("unroll") for (int m = 0; m < 4; ++m) _Pragma("unroll") for (int n = 0; n < 2; ++n) _Pragma("unroll") for (int k = 0; k < 2; ++k) \
;         acc[ai][bj][m][n] = __builtin_amdgcn_mfma_f32_16x16x32_bf16(Bt[n][k], At[m][k], acc[ai][bj][m][n], 0, 0, 0); __builtin_amdgcn_s_setprio(0); } while (0)
; #define PG8_WAIT_V(n) asm volatile("s_waitcnt vmcnt(" #n ")" ::: "memory")
; #define PG8_WAIT_L(n) asm volatile("s_waitcnt lgkmcnt(" #n ")" ::: "memory")
; #define PG8_BAR __builtin_amdgcn_s_barrier()
; #define PG8_SCHED __builtin_amdgcn_sched_barrier(0)
; template <class Epi, class Sched, bool ALIGN_EPI = false, bool SP2 = false>
; __device__ __forceinline__ void gemm_phase(PG8_LAS unsigned char* lds, const Gemm g, const Sched& S, const Epi& E, const int tid) {
;     ...
;             PG8_WAIT_V(8); PG8_WAIT_L(0); PG8_BAR; PG8_MMA(1, 0, At, B0); PG8_MMA(1, 1, At, B1); PG8_BAR; PG8_SCHED;
;             PG8_LDB(B0, 1, 0); PG8_LDB(B1, 1, 1); PG8_SCHED; PG8_LDA(At, 1, 0); PG8_STAGE(PG8_SA(0, 1), a2 + hstep, voffA);
;             PG8_WAIT_V(8); PG8_WAIT_L(0); PG8_BAR; PG8_MMA(0, 0, At, B0); PG8_MMA(0, 1, At, B1); PG8_BAR; PG8_SCHED;
	s_setprio 1
	s_waitcnt lgkmcnt(0)
	v_mfma_f32_16x16x32_bf16 v[60:63], v[144:147], v[176:179], v[60:63]
	v_mfma_f32_16x16x32_bf16 v[56:59], v[152:155], v[176:179], v[56:59]
	v_mfma_f32_16x16x32_bf16 v[44:47], v[144:147], v[184:187], v[44:47]
	v_mfma_f32_16x16x32_bf16 v[40:43], v[152:155], v[184:187], v[40:43]
	v_mfma_f32_16x16x32_bf16 v[28:31], v[144:147], v[196:199], v[28:31]
	v_mfma_f32_16x16x32_bf16 v[24:27], v[152:155], v[196:199], v[24:27]
	v_mfma_f32_16x16x32_bf16 v[12:15], v[144:147], v[204:207], v[12:15]
	v_mfma_f32_16x16x32_bf16 v[8:11], v[152:155], v[204:207], v[8:11]
	v_mfma_f32_16x16x32_bf16 v[60:63], v[148:151], v[180:183], v[60:63]
	v_mfma_f32_16x16x32_bf16 v[56:59], v[156:159], v[180:183], v[56:59]
	v_mfma_f32_16x16x32_bf16 v[44:47], v[148:151], v[188:191], v[44:47]
	v_mfma_f32_16x16x32_bf16 v[40:43], v[156:159], v[188:191], v[40:43]
	v_mfma_f32_16x16x32_bf16 v[28:31], v[148:151], v[200:203], v[28:31]
	v_mfma_f32_16x16x32_bf16 v[24:27], v[156:159], v[200:203], v[24:27]
	v_mfma_f32_16x16x32_bf16 v[12:15], v[148:151], v[208:211], v[12:15]
	v_mfma_f32_16x16x32_bf16 v[8:11], v[156:159], v[208:211], v[8:11]
	v_mfma_f32_16x16x32_bf16 v[52:55], v[160:163], v[176:179], v[52:55]
	v_mfma_f32_16x16x32_bf16 v[48:51], v[168:171], v[176:179], v[48:51]
	v_mfma_f32_16x16x32_bf16 v[36:39], v[160:163], v[184:187], v[36:39]
	v_mfma_f32_16x16x32_bf16 v[32:35], v[168:171], v[184:187], v[32:35]
	v_mfma_f32_16x16x32_bf16 v[20:23], v[160:163], v[196:199], v[20:23]
	v_mfma_f32_16x16x32_bf16 v[16:19], v[168:171], v[196:199], v[16:19]
	v_mfma_f32_16x16x32_bf16 v[4:7], v[160:163], v[204:207], v[4:7]
	v_mfma_f32_16x16x32_bf16 v[0:3], v[168:171], v[204:207], v[0:3]
	v_mfma_f32_16x16x32_bf16 v[52:55], v[164:167], v[180:183], v[52:55]
	v_mfma_f32_16x16x32_bf16 v[48:51], v[172:175], v[180:183], v[48:51]
	v_mfma_f32_16x16x32_bf16 v[36:39], v[164:167], v[188:191], v[36:39]
	v_mfma_f32_16x16x32_bf16 v[32:35], v[172:175], v[188:191], v[32:35]
	v_mfma_f32_16x16x32_bf16 v[20:23], v[164:167], v[200:203], v[20:23]
	v_mfma_f32_16x16x32_bf16 v[16:19], v[172:175], v[200:203], v[16:19]
	v_mfma_f32_16x16x32_bf16 v[4:7], v[164:167], v[208:211], v[4:7]
	v_mfma_f32_16x16x32_bf16 v[0:3], v[172:175], v[208:211], v[0:3]
	s_setprio 0
	s_barrier
	s_add_i32 s12, 0, 0x18000
	v_add_u32_e32 v143, s12, v140
	s_add_i32 s13, 0, 0x1c000
	ds_read_b128 v[144:147], v143
	ds_read_b128 v[148:151], v143 offset:1024
	ds_read_b128 v[152:155], v143 offset:2048
	ds_read_b128 v[156:159], v143 offset:3072
	v_add_u32_e32 v143, s13, v140
	ds_read_b128 v[160:163], v143
	ds_read_b128 v[164:167], v143 offset:1024
	ds_read_b128 v[168:171], v143 offset:2048
	ds_read_b128 v[172:175], v143 offset:3072
	s_add_u32 s10, s66, s30
	s_addc_u32 s11, s67, s31
	s_mov_b32 m0, s84
	v_lshl_add_u64 v[224:225], s[10:11], 0, v[132:133]
	ds_read_b128 v[176:179], v142 offset:32768
	ds_read_b128 v[180:183], v142 offset:33792
	ds_read_b128 v[184:187], v142 offset:34816
	ds_read_b128 v[188:191], v142 offset:35840
	ds_read_b128 v[196:199], v142 offset:36864
	ds_read_b128 v[200:203], v142 offset:37888
	ds_read_b128 v[204:207], v142 offset:38912
	ds_read_b128 v[208:211], v142 offset:39936
	global_load_lds_dwordx4 v[224:225], off
	v_lshl_add_u64 v[224:225], s[10:11], 0, v[130:131]
	s_mov_b32 m0, s85
	s_nop 0
	global_load_lds_dwordx4 v[224:225], off
	s_waitcnt vmcnt(8)
	s_waitcnt lgkmcnt(0)
	s_barrier
	s_setprio 1
	s_waitcnt lgkmcnt(0)
	v_mfma_f32_16x16x32_bf16 v[120:123], v[144:147], v[176:179], v[120:123]
	v_mfma_f32_16x16x32_bf16 v[124:127], v[152:155], v[176:179], v[124:127]
	v_mfma_f32_16x16x32_bf16 v[108:111], v[144:147], v[184:187], v[108:111]
	v_mfma_f32_16x16x32_bf16 v[104:107], v[152:155], v[184:187], v[104:107]
	v_mfma_f32_16x16x32_bf16 v[92:95], v[144:147], v[196:199], v[92:95]
	v_mfma_f32_16x16x32_bf16 v[88:91], v[152:155], v[196:199], v[88:91]
	v_mfma_f32_16x16x32_bf16 v[76:79], v[144:147], v[204:207], v[76:79]
	v_mfma_f32_16x16x32_bf16 v[72:75], v[152:155], v[204:207], v[72:75]
	v_mfma_f32_16x16x32_bf16 v[120:123], v[148:151], v[180:183], v[120:123]
	v_mfma_f32_16x16x32_bf16 v[124:127], v[156:159], v[180:183], v[124:127]
	v_mfma_f32_16x16x32_bf16 v[108:111], v[148:151], v[188:191], v[108:111]
	v_mfma_f32_16x16x32_bf16 v[104:107], v[156:159], v[188:191], v[104:107]
	v_mfma_f32_16x16x32_bf16 v[92:95], v[148:151], v[200:203], v[92:95]
	v_mfma_f32_16x16x32_bf16 v[88:91], v[156:159], v[200:203], v[88:91]
	v_mfma_f32_16x16x32_bf16 v[76:79], v[148:151], v[208:211], v[76:79]
	v_mfma_f32_16x16x32_bf16 v[72:75], v[156:159], v[208:211], v[72:75]
	v_mfma_f32_16x16x32_bf16 v[116:119], v[160:163], v[176:179], v[116:119]
	v_mfma_f32_16x16x32_bf16 v[112:115], v[168:171], v[176:179], v[112:115]
	v_mfma_f32_16x16x32_bf16 v[100:103], v[160:163], v[184:187], v[100:103]
	v_mfma_f32_16x16x32_bf16 v[96:99], v[168:171], v[184:187], v[96:99]
	v_mfma_f32_16x16x32_bf16 v[84:87], v[160:163], v[196:199], v[84:87]
	v_mfma_f32_16x16x32_bf16 v[80:83], v[168:171], v[196:199], v[80:83]
	v_mfma_f32_16x16x32_bf16 v[68:71], v[160:163], v[204:207], v[68:71]
	v_mfma_f32_16x16x32_bf16 v[64:67], v[168:171], v[204:207], v[64:67]
	v_mfma_f32_16x16x32_bf16 v[116:119], v[164:167], v[180:183], v[116:119]
	v_mfma_f32_16x16x32_bf16 v[112:115], v[172:175], v[180:183], v[112:115]
	v_mfma_f32_16x16x32_bf16 v[100:103], v[164:167], v[188:191], v[100:103]
	v_mfma_f32_16x16x32_bf16 v[96:99], v[172:175], v[188:191], v[96:99]
	v_mfma_f32_16x16x32_bf16 v[84:87], v[164:167], v[200:203], v[84:87]
	v_mfma_f32_16x16x32_bf16 v[80:83], v[172:175], v[200:203], v[80:83]
	v_mfma_f32_16x16x32_bf16 v[68:71], v[164:167], v[208:211], v[68:71]
	v_mfma_f32_16x16x32_bf16 v[64:67], v[172:175], v[208:211], v[64:67]
	s_setprio 0
	s_barrier
; #define PG8_STAGE(bufoff, gbase, voff) do { _Pragma("unroll") for (int _i = 0; _i < 2; ++_i) \
;         __builtin_amdgcn_global_load_lds((const unsigned*)((const char*)(gbase) + (voff)[_i]), (PG8_LAS unsigned*)(lds + (bufoff) + ldsw + _i * 8192), 16, 0, 0); } while (0)
; #define PG8_LDA(dst, b, h) do { _Pragma("unroll") for (int m = 0; m < 4; ++m) _Pragma("unroll") for (int k = 0; k < 2; ++k) dst[m][k] = *(const PG8_LAS bf16x8*)(lds + PG8_SA(b, h) + aoff + m * 2048 + k * 1024); } while (0)
; #define PG8_MMA(ai, bj, At, Bt) do { __builtin_amdgcn_s_setprio(1); _Pragma("unroll") for (int m = 0; m < 4; ++m) _Pragma("unroll") for (int n = 0; n < 2; ++n) _Pragma("unroll") for (int k = 0; k < 2; ++k) \
;         acc[ai][bj][m][n] = __builtin_amdgcn_mfma_f32_16x16x32_bf16(Bt[n][k], At[m][k], acc[ai][bj][m][n], 0, 0, 0); __builtin_amdgcn_s_setprio(0); } while (0)
; #define PG8_WAIT_V(n) asm volatile("s_waitcnt vmcnt(" #n ")" ::: "memory")
; #define PG8_WAIT_L(n) asm volatile("s_waitcnt lgkmcnt(" #n ")" ::: "memory")
; #define PG8_BAR __builtin_amdgcn_s_barrier()
; #define PG8_SCHED __builtin_amdgcn_sched_barrier(0)
; template <class Epi, class Sched, bool ALIGN_EPI = false, bool SP2 = false>
; __device__ __forceinline__ void gemm_phase(PG8_LAS unsigned char* lds, const Gemm g, const Sched& S, const Epi& E, const int tid) {
;     ...
;         for (int t = 0; t < nt; t += 2) {
;     ...
;             PG8_LDA(At, 1, 1); PG8_STAGE(PG8_SB(1, 0), b3, voffB); PG8_STAGE(PG8_SB(1, 1), b3 + hstep, voffB); PG8_STAGE(PG8_SA(1, 0), a3, voffA);
;             PG8_WAIT_V(8); PG8_WAIT_L(0); PG8_BAR; PG8_MMA(1, 0, At, B0); PG8_MMA(1, 1, At, B1); PG8_BAR; PG8_SCHED;
	s_add_i32 s10, s12, s4
	v_lshl_add_u64 v[212:213], v[212:213], 0, s[22:23]
	s_mov_b32 m0, s10
	ds_read_b128 v[176:179], v142 offset:49152
	ds_read_b128 v[180:183], v142 offset:50176
	ds_read_b128 v[184:187], v142 offset:51200
	ds_read_b128 v[188:191], v142 offset:52224
	ds_read_b128 v[196:199], v142 offset:53248
	ds_read_b128 v[200:203], v142 offset:54272
	ds_read_b128 v[204:207], v142 offset:55296
	ds_read_b128 v[208:211], v142 offset:56320
	global_load_lds_dwordx4 v[212:213], off
	v_lshl_add_u64 v[212:213], v[214:215], 0, s[22:23]
	s_add_i32 m0, s10, 0x2000
	s_add_i32 s10, s13, s4
	global_load_lds_dwordx4 v[212:213], off
	v_lshl_add_u64 v[212:213], v[216:217], 0, s[22:23]
	s_mov_b32 m0, s10
	s_nop 0
	global_load_lds_dwordx4 v[212:213], off
	v_lshl_add_u64 v[212:213], v[218:219], 0, s[22:23]
	s_add_i32 m0, s10, 0x2000
	s_nop 0
	global_load_lds_dwordx4 v[212:213], off
	v_lshl_add_u64 v[212:213], v[220:221], 0, s[22:23]
	s_mov_b32 m0, s88
	s_nop 0
	global_load_lds_dwordx4 v[212:213], off
	v_lshl_add_u64 v[212:213], v[222:223], 0, s[22:23]
	s_mov_b32 m0, s89
	s_nop 0
	global_load_lds_dwordx4 v[212:213], off
	s_waitcnt vmcnt(8)
	s_waitcnt lgkmcnt(0)
	s_barrier
	s_setprio 1
	s_waitcnt lgkmcnt(0)
	v_mfma_f32_16x16x32_bf16 v[60:63], v[144:147], v[176:179], v[60:63]
	v_mfma_f32_16x16x32_bf16 v[56:59], v[152:155], v[176:179], v[56:59]
	v_mfma_f32_16x16x32_bf16 v[44:47], v[144:147], v[184:187], v[44:47]
	v_mfma_f32_16x16x32_bf16 v[40:43], v[152:155], v[184:187], v[40:43]
	v_mfma_f32_16x16x32_bf16 v[28:31], v[144:147], v[196:199], v[28:31]
	v_mfma_f32_16x16x32_bf16 v[24:27], v[152:155], v[196:199], v[24:27]
	v_mfma_f32_16x16x32_bf16 v[12:15], v[144:147], v[204:207], v[12:15]
	v_mfma_f32_16x16x32_bf16 v[8:11], v[152:155], v[204:207], v[8:11]
	v_mfma_f32_16x16x32_bf16 v[60:63], v[148:151], v[180:183], v[60:63]
	v_mfma_f32_16x16x32_bf16 v[56:59], v[156:159], v[180:183], v[56:59]
	v_mfma_f32_16x16x32_bf16 v[44:47], v[148:151], v[188:191], v[44:47]
	v_mfma_f32_16x16x32_bf16 v[40:43], v[156:159], v[188:191], v[40:43]
	v_mfma_f32_16x16x32_bf16 v[28:31], v[148:151], v[200:203], v[28:31]
	v_mfma_f32_16x16x32_bf16 v[24:27], v[156:159], v[200:203], v[24:27]
	v_mfma_f32_16x16x32_bf16 v[12:15], v[148:151], v[208:211], v[12:15]
	v_mfma_f32_16x16x32_bf16 v[8:11], v[156:159], v[208:211], v[8:11]
	v_mfma_f32_16x16x32_bf16 v[52:55], v[160:163], v[176:179], v[52:55]
	v_mfma_f32_16x16x32_bf16 v[48:51], v[168:171], v[176:179], v[48:51]
	v_mfma_f32_16x16x32_bf16 v[36:39], v[160:163], v[184:187], v[36:39]
	v_mfma_f32_16x16x32_bf16 v[32:35], v[168:171], v[184:187], v[32:35]
	v_mfma_f32_16x16x32_bf16 v[20:23], v[160:163], v[196:199], v[20:23]
	v_mfma_f32_16x16x32_bf16 v[16:19], v[168:171], v[196:199], v[16:19]
	v_mfma_f32_16x16x32_bf16 v[4:7], v[160:163], v[204:207], v[4:7]
	v_mfma_f32_16x16x32_bf16 v[0:3], v[168:171], v[204:207], v[0:3]
	v_mfma_f32_16x16x32_bf16 v[52:55], v[164:167], v[180:183], v[52:55]
	v_mfma_f32_16x16x32_bf16 v[48:51], v[172:175], v[180:183], v[48:51]
	v_mfma_f32_16x16x32_bf16 v[36:39], v[164:167], v[188:191], v[36:39]
	v_mfma_f32_16x16x32_bf16 v[32:35], v[172:175], v[188:191], v[32:35]
	v_mfma_f32_16x16x32_bf16 v[20:23], v[164:167], v[200:203], v[20:23]
	v_mfma_f32_16x16x32_bf16 v[16:19], v[172:175], v[200:203], v[16:19]
	v_mfma_f32_16x16x32_bf16 v[4:7], v[164:167], v[208:211], v[4:7]
	v_mfma_f32_16x16x32_bf16 v[0:3], v[172:175], v[208:211], v[0:3]
	s_setprio 0
	s_barrier
	s_add_u32 s0, s0, 0x100
	s_addc_u32 s1, s1, 0
	s_add_u32 s8, s8, 0x100
	s_addc_u32 s9, s9, 0
	s_cmp_ge_i32 vcc_lo, s86
	s_mov_b32 s66, vcc_lo
	s_cbranch_scc0 .LBB0_144

; #define PG8_STAGE(bufoff, gbase, voff) do { _Pragma("unroll") for (int _i = 0; _i < 2; ++_i) \
;         __builtin_amdgcn_global_load_lds((const unsigned*)((const char*)(gbase) + (voff)[_i]), (PG8_LAS unsigned*)(lds + (bufoff) + ldsw + _i * 8192), 16, 0, 0); } while (0)
; #define PG8_LDA(dst, b, h) do { _Pragma("unroll") for (int m = 0; m < 4; ++m) _Pragma("unroll") for (int k = 0; k < 2; ++k) dst[m][k] = *(const PG8_LAS bf16x8*)(lds + PG8_SA(b, h) + aoff + m * 2048 + k * 1024); } while (0)
; #define PG8_LDB(dst, b, h) do { _Pragma("unroll") for (int n = 0; n < 2; ++n) _Pragma("unroll") for (int k = 0; k < 2; ++k) dst[n][k] = *(const PG8_LAS bf16x8*)(lds + PG8_SB(b, h) + boff + n * 2048 + k * 1024); } while (0)
; #define PG8_MMA(ai, bj, At, Bt) do { __builtin_amdgcn_s_setprio(1); _Pragma("unroll") for (int m = 0; m < 4; ++m) _Pragma("unroll") for (int n = 0; n < 2; ++n) _Pragma("unroll") for (int k = 0; k < 2; ++k) \
;         acc[ai][bj][m][n] = __builtin_amdgcn_mfma_f32_16x16x32_bf16(Bt[n][k], At[m][k], acc[ai][bj][m][n], 0, 0, 0); __builtin_amdgcn_s_setprio(0); } while (0)
; #define PG8_WAIT_V(n) asm volatile("s_waitcnt vmcnt(" #n ")" ::: "memory")
; #define PG8_WAIT_L(n) asm volatile("s_waitcnt lgkmcnt(" #n ")" ::: "memory")
; #define PG8_BAR __builtin_amdgcn_s_barrier()
; #define PG8_SCHED __builtin_amdgcn_sched_barrier(0)
; template <class Epi, class Sched, bool ALIGN_EPI = false, bool SP2 = false>
; __device__ __forceinline__ void gemm_phase(PG8_LAS unsigned char* lds, const Gemm g, const Sched& S, const Epi& E, const int tid) {
;     ...
;             PG8_LDB(B0, 0, 0); PG8_LDB(B1, 0, 1); PG8_SCHED; PG8_LDA(At, 0, 0); PG8_STAGE(PG8_SA(1, 1), a1 + hstep, voffA);
;             PG8_WAIT_V(8); PG8_WAIT_L(0); PG8_BAR; PG8_MMA(0, 0, At, B0); PG8_MMA(0, 1, At, B1); PG8_BAR; PG8_SCHED;
;             PG8_LDA(At, 0, 1); PG8_STAGE(PG8_SB(0, 0), b2, voffB); PG8_STAGE(PG8_SB(0, 1), b2 + hstep, voffB); PG8_STAGE(PG8_SA(0, 0), a2, voffA);
;             PG8_WAIT_V(8); PG8_WAIT_L(0); PG8_BAR; PG8_MMA(1, 0, At, B0); PG8_MMA(1, 1, At, B1); PG8_BAR; PG8_SCHED;
.LBB0_166:
	s_add_u32 s10, s0, 0xfffc0080
	s_addc_u32 s11, s1, -1
	s_add_i32 s12, 0, 0x10000
	s_cmp_eq_u32 s9, 12
	s_cselect_b32 s87, s31, s11
	s_cselect_b32 s86, s43, s10
	s_cselect_b32 s53, s65, s8
	s_cselect_b32 s52, s67, s82
	s_add_i32 s13, 0, 0x14000
	v_add_u32_e32 v124, s12, v224
	v_add_u32_e32 v152, s13, v224
	ds_read_b128 v[112:115], v124
	ds_read_b128 v[116:119], v124 offset:1024
	ds_read_b128 v[120:123], v124 offset:2048
	ds_read_b128 v[124:127], v124 offset:3072
	ds_read_b128 v[140:143], v152
	ds_read_b128 v[144:147], v152 offset:1024
	ds_read_b128 v[148:151], v152 offset:2048
	ds_read_b128 v[152:155], v152 offset:3072
	v_lshl_add_u64 v[206:207], s[0:1], 0, v[202:203]
	s_add_i32 m0, s7, 0xc000
	ds_read_b128 v[160:163], v228
	ds_read_b128 v[164:167], v228 offset:1024
	ds_read_b128 v[168:171], v228 offset:2048
	ds_read_b128 v[172:175], v228 offset:3072
	ds_read_b128 v[176:179], v228 offset:4096
	ds_read_b128 v[180:183], v228 offset:5120
	ds_read_b128 v[184:187], v228 offset:6144
	ds_read_b128 v[188:191], v228 offset:7168
	global_load_lds_dwordx4 v[206:207], off
	v_lshl_add_u64 v[206:207], s[0:1], 0, v[204:205]
	s_add_i32 m0, s7, 0xe000
	s_nop 0
	global_load_lds_dwordx4 v[206:207], off
	s_waitcnt vmcnt(8)
	s_waitcnt lgkmcnt(0)
	s_barrier
	s_setprio 1
	s_waitcnt lgkmcnt(0)
	v_mfma_f32_16x16x32_bf16 v[156:159], v[112:115], v[160:163], v[156:159]
	v_mfma_f32_16x16x32_bf16 v[136:139], v[120:123], v[160:163], v[136:139]
	v_mfma_f32_16x16x32_bf16 v[108:111], v[112:115], v[168:171], v[108:111]
	v_mfma_f32_16x16x32_bf16 v[104:107], v[120:123], v[168:171], v[104:107]
	v_mfma_f32_16x16x32_bf16 v[92:95], v[112:115], v[176:179], v[92:95]
	v_mfma_f32_16x16x32_bf16 v[88:91], v[120:123], v[176:179], v[88:91]
	v_mfma_f32_16x16x32_bf16 v[76:79], v[112:115], v[184:187], v[76:79]
	v_mfma_f32_16x16x32_bf16 v[72:75], v[120:123], v[184:187], v[72:75]
	v_mfma_f32_16x16x32_bf16 v[156:159], v[116:119], v[164:167], v[156:159]
	v_mfma_f32_16x16x32_bf16 v[136:139], v[124:127], v[164:167], v[136:139]
	v_mfma_f32_16x16x32_bf16 v[108:111], v[116:119], v[172:175], v[108:111]
	v_mfma_f32_16x16x32_bf16 v[104:107], v[124:127], v[172:175], v[104:107]
	v_mfma_f32_16x16x32_bf16 v[92:95], v[116:119], v[180:183], v[92:95]
	v_mfma_f32_16x16x32_bf16 v[88:91], v[124:127], v[180:183], v[88:91]
	v_mfma_f32_16x16x32_bf16 v[76:79], v[116:119], v[188:191], v[76:79]
	v_mfma_f32_16x16x32_bf16 v[72:75], v[124:127], v[188:191], v[72:75]
	v_mfma_f32_16x16x32_bf16 v[132:135], v[140:143], v[160:163], v[132:135]
	v_mfma_f32_16x16x32_bf16 v[128:131], v[148:151], v[160:163], v[128:131]
	v_mfma_f32_16x16x32_bf16 v[100:103], v[140:143], v[168:171], v[100:103]
	v_mfma_f32_16x16x32_bf16 v[96:99], v[148:151], v[168:171], v[96:99]
	v_mfma_f32_16x16x32_bf16 v[84:87], v[140:143], v[176:179], v[84:87]
	v_mfma_f32_16x16x32_bf16 v[80:83], v[148:151], v[176:179], v[80:83]
	v_mfma_f32_16x16x32_bf16 v[68:71], v[140:143], v[184:187], v[68:71]
	v_mfma_f32_16x16x32_bf16 v[64:67], v[148:151], v[184:187], v[64:67]
	v_mfma_f32_16x16x32_bf16 v[132:135], v[144:147], v[164:167], v[132:135]
	v_mfma_f32_16x16x32_bf16 v[128:131], v[152:155], v[164:167], v[128:131]
	v_mfma_f32_16x16x32_bf16 v[100:103], v[144:147], v[172:175], v[100:103]
	v_mfma_f32_16x16x32_bf16 v[96:99], v[152:155], v[172:175], v[96:99]
	v_mfma_f32_16x16x32_bf16 v[84:87], v[144:147], v[180:183], v[84:87]
	v_mfma_f32_16x16x32_bf16 v[80:83], v[152:155], v[180:183], v[80:83]
	v_mfma_f32_16x16x32_bf16 v[68:71], v[144:147], v[188:191], v[68:71]
	v_mfma_f32_16x16x32_bf16 v[64:67], v[152:155], v[188:191], v[64:67]
	s_setprio 0
	s_barrier
	s_add_i32 s10, s12, s4
	v_lshl_add_u64 v[206:207], s[52:53], 0, v[192:193]
	s_mov_b32 m0, s10
	ds_read_b128 v[160:163], v228 offset:16384
	ds_read_b128 v[164:167], v228 offset:17408
	ds_read_b128 v[168:171], v228 offset:18432
	ds_read_b128 v[172:175], v228 offset:19456
	ds_read_b128 v[176:179], v228 offset:20480
	ds_read_b128 v[180:183], v228 offset:21504
	ds_read_b128 v[184:187], v228 offset:22528
	ds_read_b128 v[188:191], v228 offset:23552
	global_load_lds_dwordx4 v[206:207], off
	s_add_i32 m0, s10, 0x2000
	s_add_u32 s10, s52, 0x40000
	v_lshl_add_u64 v[208:209], s[52:53], 0, v[200:201]
	s_addc_u32 s11, s53, 0
	s_add_i32 s12, s13, s4
	global_load_lds_dwordx4 v[208:209], off
	v_lshl_add_u64 v[210:211], s[10:11], 0, v[192:193]
	s_mov_b32 m0, s12
	v_lshl_add_u64 v[212:213], s[86:87], 0, v[198:199]
	global_load_lds_dwordx4 v[210:211], off
	v_lshl_add_u64 v[210:211], s[10:11], 0, v[200:201]
	s_add_i32 m0, s12, 0x2000
	s_nop 0
	global_load_lds_dwordx4 v[210:211], off
	v_lshl_add_u64 v[210:211], s[86:87], 0, v[196:197]
	s_mov_b32 m0, s7
	s_nop 0
	global_load_lds_dwordx4 v[210:211], off
	s_mov_b32 m0, s76
	s_nop 0
	global_load_lds_dwordx4 v[212:213], off
	s_waitcnt vmcnt(8)
	s_waitcnt lgkmcnt(0)
	s_barrier
; #define PG8_STAGE(bufoff, gbase, voff) do { _Pragma("unroll") for (int _i = 0; _i < 2; ++_i) \
;         __builtin_amdgcn_global_load_lds((const unsigned*)((const char*)(gbase) + (voff)[_i]), (PG8_LAS unsigned*)(lds + (bufoff) + ldsw + _i * 8192), 16, 0, 0); } while (0)
; #define PG8_LDA(dst, b, h) do { _Pragma("unroll") for (int m = 0; m < 4; ++m) _Pragma("unroll") for (int k = 0; k < 2; ++k) dst[m][k] = *(const PG8_LAS bf16x8*)(lds + PG8_SA(b, h) + aoff + m * 2048 + k * 1024); } while (0)
; #define PG8_LDB(dst, b, h) do { _Pragma("unroll") for (int n = 0; n < 2; ++n) _Pragma("unroll") for (int k = 0; k < 2; ++k) dst[n][k] = *(const PG8_LAS bf16x8*)(lds + PG8_SB(b, h) + boff + n * 2048 + k * 1024); } while (0)
; #define PG8_MMA(ai, bj, At, Bt) do { __builtin_amdgcn_s_setprio(1); _Pragma("unroll") for (int m = 0; m < 4; ++m) _Pragma("unroll") for (int n = 0; n < 2; ++n) _Pragma("unroll") for (int k = 0; k < 2; ++k) \
;         acc[ai][bj][m][n] = __builtin_amdgcn_mfma_f32_16x16x32_bf16(Bt[n][k], At[m][k], acc[ai][bj][m][n], 0, 0, 0); __builtin_amdgcn_s_setprio(0); } while (0)
; #define PG8_WAIT_V(n) asm volatile("s_waitcnt vmcnt(" #n ")" ::: "memory")
; #define PG8_WAIT_L(n) asm volatile("s_waitcnt lgkmcnt(" #n ")" ::: "memory")
; #define PG8_BAR __builtin_amdgcn_s_barrier()
; #define PG8_SCHED __builtin_amdgcn_sched_barrier(0)
; template <class Epi, class Sched, bool ALIGN_EPI = false, bool SP2 = false>
; __device__ __forceinline__ void gemm_phase(PG8_LAS unsigned char* lds, const Gemm g, const Sched& S, const Epi& E, const int tid) {
;     ...
;             PG8_WAIT_V(8); PG8_WAIT_L(0); PG8_BAR; PG8_MMA(1, 0, At, B0); PG8_MMA(1, 1, At, B1); PG8_BAR; PG8_SCHED;
;             PG8_LDB(B0, 1, 0); PG8_LDB(B1, 1, 1); PG8_SCHED; PG8_LDA(At, 1, 0); PG8_STAGE(PG8_SA(0, 1), a2 + hstep, voffA);
;             PG8_WAIT_V(8); PG8_WAIT_L(0); PG8_BAR; PG8_MMA(0, 0, At, B0); PG8_MMA(0, 1, At, B1); PG8_BAR; PG8_SCHED;
	s_setprio 1
	s_waitcnt lgkmcnt(0)
	v_mfma_f32_16x16x32_bf16 v[60:63], v[112:115], v[160:163], v[60:63]
	v_mfma_f32_16x16x32_bf16 v[56:59], v[120:123], v[160:163], v[56:59]
	v_mfma_f32_16x16x32_bf16 v[44:47], v[112:115], v[168:171], v[44:47]
	v_mfma_f32_16x16x32_bf16 v[40:43], v[120:123], v[168:171], v[40:43]
	v_mfma_f32_16x16x32_bf16 v[28:31], v[112:115], v[176:179], v[28:31]
	v_mfma_f32_16x16x32_bf16 v[24:27], v[120:123], v[176:179], v[24:27]
	v_mfma_f32_16x16x32_bf16 v[12:15], v[112:115], v[184:187], v[12:15]
	v_mfma_f32_16x16x32_bf16 v[8:11], v[120:123], v[184:187], v[8:11]
	v_mfma_f32_16x16x32_bf16 v[60:63], v[116:119], v[164:167], v[60:63]
	v_mfma_f32_16x16x32_bf16 v[56:59], v[124:127], v[164:167], v[56:59]
	v_mfma_f32_16x16x32_bf16 v[44:47], v[116:119], v[172:175], v[44:47]
	v_mfma_f32_16x16x32_bf16 v[40:43], v[124:127], v[172:175], v[40:43]
	v_mfma_f32_16x16x32_bf16 v[28:31], v[116:119], v[180:183], v[28:31]
	v_mfma_f32_16x16x32_bf16 v[24:27], v[124:127], v[180:183], v[24:27]
	v_mfma_f32_16x16x32_bf16 v[12:15], v[116:119], v[188:191], v[12:15]
	v_mfma_f32_16x16x32_bf16 v[8:11], v[124:127], v[188:191], v[8:11]
	v_mfma_f32_16x16x32_bf16 v[52:55], v[140:143], v[160:163], v[52:55]
	v_mfma_f32_16x16x32_bf16 v[48:51], v[148:151], v[160:163], v[48:51]
	v_mfma_f32_16x16x32_bf16 v[36:39], v[140:143], v[168:171], v[36:39]
	v_mfma_f32_16x16x32_bf16 v[32:35], v[148:151], v[168:171], v[32:35]
	v_mfma_f32_16x16x32_bf16 v[20:23], v[140:143], v[176:179], v[20:23]
	v_mfma_f32_16x16x32_bf16 v[16:19], v[148:151], v[176:179], v[16:19]
	v_mfma_f32_16x16x32_bf16 v[4:7], v[140:143], v[184:187], v[4:7]
	v_mfma_f32_16x16x32_bf16 v[0:3], v[148:151], v[184:187], v[0:3]
	v_mfma_f32_16x16x32_bf16 v[52:55], v[144:147], v[164:167], v[52:55]
	v_mfma_f32_16x16x32_bf16 v[48:51], v[152:155], v[164:167], v[48:51]
	v_mfma_f32_16x16x32_bf16 v[36:39], v[144:147], v[172:175], v[36:39]
	v_mfma_f32_16x16x32_bf16 v[32:35], v[152:155], v[172:175], v[32:35]
	v_mfma_f32_16x16x32_bf16 v[20:23], v[144:147], v[180:183], v[20:23]
	v_mfma_f32_16x16x32_bf16 v[16:19], v[152:155], v[180:183], v[16:19]
	v_mfma_f32_16x16x32_bf16 v[4:7], v[144:147], v[188:191], v[4:7]
	v_mfma_f32_16x16x32_bf16 v[0:3], v[152:155], v[188:191], v[0:3]
	s_setprio 0
	s_barrier
	s_add_i32 s12, 0, 0x18000
	s_add_i32 s13, 0, 0x1c000
	v_add_u32_e32 v124, s12, v224
	v_add_u32_e32 v152, s13, v224
	ds_read_b128 v[112:115], v124
	ds_read_b128 v[116:119], v124 offset:1024
	ds_read_b128 v[120:123], v124 offset:2048
	ds_read_b128 v[124:127], v124 offset:3072
	ds_read_b128 v[140:143], v152
	ds_read_b128 v[144:147], v152 offset:1024
	ds_read_b128 v[148:151], v152 offset:2048
	ds_read_b128 v[152:155], v152 offset:3072
	s_add_u32 s10, s86, 0x40000
	s_addc_u32 s11, s87, 0
	s_mov_b32 m0, s77
	v_lshl_add_u64 v[214:215], s[10:11], 0, v[196:197]
	ds_read_b128 v[160:163], v228 offset:32768
	ds_read_b128 v[164:167], v228 offset:33792
	ds_read_b128 v[168:171], v228 offset:34816
	ds_read_b128 v[172:175], v228 offset:35840
	ds_read_b128 v[176:179], v228 offset:36864
	ds_read_b128 v[180:183], v228 offset:37888
	ds_read_b128 v[184:187], v228 offset:38912
	ds_read_b128 v[188:191], v228 offset:39936
	global_load_lds_dwordx4 v[214:215], off
	v_lshl_add_u64 v[214:215], s[10:11], 0, v[198:199]
	s_mov_b32 m0, s96
	s_nop 0
	global_load_lds_dwordx4 v[214:215], off
	s_waitcnt vmcnt(8)
	s_waitcnt lgkmcnt(0)
	s_barrier
	s_setprio 1
	s_waitcnt lgkmcnt(0)
	v_mfma_f32_16x16x32_bf16 v[156:159], v[112:115], v[160:163], v[156:159]
	v_mfma_f32_16x16x32_bf16 v[136:139], v[120:123], v[160:163], v[136:139]
	v_mfma_f32_16x16x32_bf16 v[108:111], v[112:115], v[168:171], v[108:111]
	v_mfma_f32_16x16x32_bf16 v[104:107], v[120:123], v[168:171], v[104:107]
	v_mfma_f32_16x16x32_bf16 v[92:95], v[112:115], v[176:179], v[92:95]
	v_mfma_f32_16x16x32_bf16 v[88:91], v[120:123], v[176:179], v[88:91]
	v_mfma_f32_16x16x32_bf16 v[76:79], v[112:115], v[184:187], v[76:79]
	v_mfma_f32_16x16x32_bf16 v[72:75], v[120:123], v[184:187], v[72:75]
	v_mfma_f32_16x16x32_bf16 v[156:159], v[116:119], v[164:167], v[156:159]
	v_mfma_f32_16x16x32_bf16 v[136:139], v[124:127], v[164:167], v[136:139]
	v_mfma_f32_16x16x32_bf16 v[108:111], v[116:119], v[172:175], v[108:111]
	v_mfma_f32_16x16x32_bf16 v[104:107], v[124:127], v[172:175], v[104:107]
	v_mfma_f32_16x16x32_bf16 v[92:95], v[116:119], v[180:183], v[92:95]
	v_mfma_f32_16x16x32_bf16 v[88:91], v[124:127], v[180:183], v[88:91]
	v_mfma_f32_16x16x32_bf16 v[76:79], v[116:119], v[188:191], v[76:79]
	v_mfma_f32_16x16x32_bf16 v[72:75], v[124:127], v[188:191], v[72:75]
	v_mfma_f32_16x16x32_bf16 v[132:135], v[140:143], v[160:163], v[132:135]
	v_mfma_f32_16x16x32_bf16 v[128:131], v[148:151], v[160:163], v[128:131]
	v_mfma_f32_16x16x32_bf16 v[100:103], v[140:143], v[168:171], v[100:103]
	v_mfma_f32_16x16x32_bf16 v[96:99], v[148:151], v[168:171], v[96:99]
	v_mfma_f32_16x16x32_bf16 v[84:87], v[140:143], v[176:179], v[84:87]
	v_mfma_f32_16x16x32_bf16 v[80:83], v[148:151], v[176:179], v[80:83]
	v_mfma_f32_16x16x32_bf16 v[68:71], v[140:143], v[184:187], v[68:71]
	v_mfma_f32_16x16x32_bf16 v[64:67], v[148:151], v[184:187], v[64:67]
	v_mfma_f32_16x16x32_bf16 v[132:135], v[144:147], v[164:167], v[132:135]
	v_mfma_f32_16x16x32_bf16 v[128:131], v[152:155], v[164:167], v[128:131]
	v_mfma_f32_16x16x32_bf16 v[100:103], v[144:147], v[172:175], v[100:103]
	v_mfma_f32_16x16x32_bf16 v[96:99], v[152:155], v[172:175], v[96:99]
	v_mfma_f32_16x16x32_bf16 v[84:87], v[144:147], v[180:183], v[84:87]
	v_mfma_f32_16x16x32_bf16 v[80:83], v[152:155], v[180:183], v[80:83]
	v_mfma_f32_16x16x32_bf16 v[68:71], v[144:147], v[188:191], v[68:71]
	v_mfma_f32_16x16x32_bf16 v[64:67], v[152:155], v[188:191], v[64:67]
	s_setprio 0
	s_barrier
; #define PG8_STAGE(bufoff, gbase, voff) do { _Pragma("unroll") for (int _i = 0; _i < 2; ++_i) \
;         __builtin_amdgcn_global_load_lds((const unsigned*)((const char*)(gbase) + (voff)[_i]), (PG8_LAS unsigned*)(lds + (bufoff) + ldsw + _i * 8192), 16, 0, 0); } while (0)
; #define PG8_LDA(dst, b, h) do { _Pragma("unroll") for (int m = 0; m < 4; ++m) _Pragma("unroll") for (int k = 0; k < 2; ++k) dst[m][k] = *(const PG8_LAS bf16x8*)(lds + PG8_SA(b, h) + aoff + m * 2048 + k * 1024); } while (0)
; #define PG8_MMA(ai, bj, At, Bt) do { __builtin_amdgcn_s_setprio(1); _Pragma("unroll") for (int m = 0; m < 4; ++m) _Pragma("unroll") for (int n = 0; n < 2; ++n) _Pragma("unroll") for (int k = 0; k < 2; ++k) \
;         acc[ai][bj][m][n] = __builtin_amdgcn_mfma_f32_16x16x32_bf16(Bt[n][k], At[m][k], acc[ai][bj][m][n], 0, 0, 0); __builtin_amdgcn_s_setprio(0); } while (0)
; #define PG8_WAIT_V(n) asm volatile("s_waitcnt vmcnt(" #n ")" ::: "memory")
; #define PG8_WAIT_L(n) asm volatile("s_waitcnt lgkmcnt(" #n ")" ::: "memory")
; #define PG8_BAR __builtin_amdgcn_s_barrier()
; #define PG8_SCHED __builtin_amdgcn_sched_barrier(0)
; template <class Epi, class Sched, bool ALIGN_EPI = false, bool SP2 = false>
; __device__ __forceinline__ void gemm_phase(PG8_LAS unsigned char* lds, const Gemm g, const Sched& S, const Epi& E, const int tid) {
;     ...
;             PG8_LDA(At, 1, 1); PG8_STAGE(PG8_SB(1, 0), b3, voffB); PG8_STAGE(PG8_SB(1, 1), b3 + hstep, voffB); PG8_STAGE(PG8_SA(1, 0), a3, voffA);
;             PG8_WAIT_V(8); PG8_WAIT_L(0); PG8_BAR; PG8_MMA(1, 0, At, B0); PG8_MMA(1, 1, At, B1); PG8_BAR; PG8_SCHED;
;     ...
;         if constexpr (ALIGN_EPI) { if (wr == 0) PG8_BAR; }
	s_add_i32 s10, s12, s4
	v_lshl_add_u64 v[206:207], v[206:207], 0, s[22:23]
	s_mov_b32 m0, s10
	ds_read_b128 v[160:163], v228 offset:49152
	ds_read_b128 v[164:167], v228 offset:50176
	ds_read_b128 v[168:171], v228 offset:51200
	ds_read_b128 v[172:175], v228 offset:52224
	ds_read_b128 v[176:179], v228 offset:53248
	ds_read_b128 v[180:183], v228 offset:54272
	ds_read_b128 v[184:187], v228 offset:55296
	ds_read_b128 v[188:191], v228 offset:56320
	global_load_lds_dwordx4 v[206:207], off
	s_add_i32 m0, s10, 0x2000
	s_add_u32 s10, s52, 0x40080
	v_lshl_add_u64 v[206:207], v[208:209], 0, s[22:23]
	s_addc_u32 s11, s53, 0
	s_add_i32 s12, s13, s4
	global_load_lds_dwordx4 v[206:207], off
	v_lshl_add_u64 v[206:207], s[10:11], 0, v[192:193]
	s_mov_b32 m0, s12
	s_nop 0
	global_load_lds_dwordx4 v[206:207], off
	v_lshl_add_u64 v[206:207], s[10:11], 0, v[200:201]
	s_add_i32 m0, s12, 0x2000
	s_nop 0
	global_load_lds_dwordx4 v[206:207], off
	v_lshl_add_u64 v[206:207], v[210:211], 0, s[22:23]
	s_mov_b32 m0, s89
	s_nop 0
	global_load_lds_dwordx4 v[206:207], off
	v_lshl_add_u64 v[206:207], v[212:213], 0, s[22:23]
	s_mov_b32 m0, s95
	s_nop 0
	global_load_lds_dwordx4 v[206:207], off
	s_waitcnt vmcnt(8)
	s_waitcnt lgkmcnt(0)
	s_barrier
	s_setprio 1
	s_waitcnt lgkmcnt(0)
	v_mfma_f32_16x16x32_bf16 v[60:63], v[112:115], v[160:163], v[60:63]
	v_mfma_f32_16x16x32_bf16 v[56:59], v[120:123], v[160:163], v[56:59]
	v_mfma_f32_16x16x32_bf16 v[44:47], v[112:115], v[168:171], v[44:47]
	v_mfma_f32_16x16x32_bf16 v[40:43], v[120:123], v[168:171], v[40:43]
	v_mfma_f32_16x16x32_bf16 v[28:31], v[112:115], v[176:179], v[28:31]
	v_mfma_f32_16x16x32_bf16 v[24:27], v[120:123], v[176:179], v[24:27]
	v_mfma_f32_16x16x32_bf16 v[12:15], v[112:115], v[184:187], v[12:15]
	v_mfma_f32_16x16x32_bf16 v[8:11], v[120:123], v[184:187], v[8:11]
	v_mfma_f32_16x16x32_bf16 v[60:63], v[116:119], v[164:167], v[60:63]
	v_mfma_f32_16x16x32_bf16 v[56:59], v[124:127], v[164:167], v[56:59]
	v_mfma_f32_16x16x32_bf16 v[44:47], v[116:119], v[172:175], v[44:47]
	v_mfma_f32_16x16x32_bf16 v[40:43], v[124:127], v[172:175], v[40:43]
	v_mfma_f32_16x16x32_bf16 v[28:31], v[116:119], v[180:183], v[28:31]
	v_mfma_f32_16x16x32_bf16 v[24:27], v[124:127], v[180:183], v[24:27]
	v_mfma_f32_16x16x32_bf16 v[12:15], v[116:119], v[188:191], v[12:15]
	v_mfma_f32_16x16x32_bf16 v[8:11], v[124:127], v[188:191], v[8:11]
	v_mfma_f32_16x16x32_bf16 v[52:55], v[140:143], v[160:163], v[52:55]
	v_mfma_f32_16x16x32_bf16 v[48:51], v[148:151], v[160:163], v[48:51]
	v_mfma_f32_16x16x32_bf16 v[36:39], v[140:143], v[168:171], v[36:39]
	v_mfma_f32_16x16x32_bf16 v[32:35], v[148:151], v[168:171], v[32:35]
	v_mfma_f32_16x16x32_bf16 v[20:23], v[140:143], v[176:179], v[20:23]
	v_mfma_f32_16x16x32_bf16 v[16:19], v[148:151], v[176:179], v[16:19]
	v_mfma_f32_16x16x32_bf16 v[4:7], v[140:143], v[184:187], v[4:7]
	v_mfma_f32_16x16x32_bf16 v[0:3], v[148:151], v[184:187], v[0:3]
	v_mfma_f32_16x16x32_bf16 v[52:55], v[144:147], v[164:167], v[52:55]
	v_mfma_f32_16x16x32_bf16 v[48:51], v[152:155], v[164:167], v[48:51]
	v_mfma_f32_16x16x32_bf16 v[36:39], v[144:147], v[172:175], v[36:39]
	v_mfma_f32_16x16x32_bf16 v[32:35], v[152:155], v[172:175], v[32:35]
	v_mfma_f32_16x16x32_bf16 v[20:23], v[144:147], v[180:183], v[20:23]
	v_mfma_f32_16x16x32_bf16 v[16:19], v[152:155], v[180:183], v[16:19]
	v_mfma_f32_16x16x32_bf16 v[4:7], v[144:147], v[188:191], v[4:7]
	v_mfma_f32_16x16x32_bf16 v[0:3], v[152:155], v[188:191], v[0:3]
	s_setprio 0
	s_barrier
	s_add_i32 s9, s9, 2
	s_add_u32 s0, s0, 0x100
	s_addc_u32 s1, s1, 0
	s_add_u32 s82, s82, 0x100
	s_addc_u32 s8, s8, 0
	s_cmp_gt_u32 s9, 13
	s_cbranch_scc0 .LBB0_166
	s_and_b64 vcc, exec, s[60:61]
	s_cbranch_vccz .LBB0_169
	s_barrier

; #define PG8_STAGE(bufoff, gbase, voff) do { _Pragma("unroll") for (int _i = 0; _i < 2; ++_i) \
;         __builtin_amdgcn_global_load_lds((const unsigned*)((const char*)(gbase) + (voff)[_i]), (PG8_LAS unsigned*)(lds + (bufoff) + ldsw + _i * 8192), 16, 0, 0); } while (0)
; #define PG8_LDA(dst, b, h) do { _Pragma("unroll") for (int m = 0; m < 4; ++m) _Pragma("unroll") for (int k = 0; k < 2; ++k) dst[m][k] = *(const PG8_LAS bf16x8*)(lds + PG8_SA(b, h) + aoff + m * 2048 + k * 1024); } while (0)
; #define PG8_LDB(dst, b, h) do { _Pragma("unroll") for (int n = 0; n < 2; ++n) _Pragma("unroll") for (int k = 0; k < 2; ++k) dst[n][k] = *(const PG8_LAS bf16x8*)(lds + PG8_SB(b, h) + boff + n * 2048 + k * 1024); } while (0)
; #define PG8_MMA(ai, bj, At, Bt) do { __builtin_amdgcn_s_setprio(1); _Pragma("unroll") for (int m = 0; m < 4; ++m) _Pragma("unroll") for (int n = 0; n < 2; ++n) _Pragma("unroll") for (int k = 0; k < 2; ++k) \
;         acc[ai][bj][m][n] = __builtin_amdgcn_mfma_f32_16x16x32_bf16(Bt[n][k], At[m][k], acc[ai][bj][m][n], 0, 0, 0); __builtin_amdgcn_s_setprio(0); } while (0)
; #define PG8_WAIT_V(n) asm volatile("s_waitcnt vmcnt(" #n ")" ::: "memory")
; #define PG8_WAIT_L(n) asm volatile("s_waitcnt lgkmcnt(" #n ")" ::: "memory")
; #define PG8_BAR __builtin_amdgcn_s_barrier()
; #define PG8_SCHED __builtin_amdgcn_sched_barrier(0)
; template <class Epi, class Sched, bool ALIGN_EPI = false, bool SP2 = false>
; __device__ __forceinline__ void gemm_phase(PG8_LAS unsigned char* lds, const Gemm g, const Sched& S, const Epi& E, const int tid) {
;     ...
;             PG8_LDB(B0, 0, 0); PG8_LDB(B1, 0, 1); PG8_SCHED; PG8_LDA(At, 0, 0); PG8_STAGE(PG8_SA(1, 1), a1 + hstep, voffA);
;             PG8_WAIT_V(8); PG8_WAIT_L(0); PG8_BAR; PG8_MMA(0, 0, At, B0); PG8_MMA(0, 1, At, B1); PG8_BAR; PG8_SCHED;
;             PG8_LDA(At, 0, 1); PG8_STAGE(PG8_SB(0, 0), b2, voffB); PG8_STAGE(PG8_SB(0, 1), b2 + hstep, voffB); PG8_STAGE(PG8_SA(0, 0), a2, voffA);
;             PG8_WAIT_V(8); PG8_WAIT_L(0); PG8_BAR; PG8_MMA(1, 0, At, B0); PG8_MMA(1, 1, At, B1); PG8_BAR; PG8_SCHED;
.LBB0_236:
	s_add_u32 s10, s58, 0xfff00080
	s_addc_u32 s11, s59, -1
	s_add_i32 s12, 0, 0x10000
	s_cmp_eq_u32 s9, 60
	s_cselect_b32 s65, s53, s11
	s_cselect_b32 s64, s85, s10
	s_cselect_b32 s61, s43, s8
	s_cselect_b32 s60, s86, s87
	s_add_i32 s13, 0, 0x14000
	v_add_u32_e32 v140, s12, v218
	v_add_u32_e32 v156, s13, v218
	ds_read_b128 v[128:131], v140
	ds_read_b128 v[132:135], v140 offset:1024
	ds_read_b128 v[136:139], v140 offset:2048
	ds_read_b128 v[140:143], v140 offset:3072
	ds_read_b128 v[144:147], v156
	ds_read_b128 v[148:151], v156 offset:1024
	ds_read_b128 v[152:155], v156 offset:2048
	ds_read_b128 v[156:159], v156 offset:3072
	v_lshl_add_u64 v[206:207], s[58:59], 0, v[198:199]
	s_add_i32 m0, s7, 0xc000
	ds_read_b128 v[160:163], v220
	ds_read_b128 v[164:167], v220 offset:1024
	ds_read_b128 v[168:171], v220 offset:2048
	ds_read_b128 v[172:175], v220 offset:3072
	ds_read_b128 v[176:179], v220 offset:4096
	ds_read_b128 v[180:183], v220 offset:5120
	ds_read_b128 v[184:187], v220 offset:6144
	ds_read_b128 v[202:205], v220 offset:7168
	global_load_lds_dwordx4 v[206:207], off
	v_lshl_add_u64 v[206:207], s[58:59], 0, v[200:201]
	s_add_i32 m0, s7, 0xe000
	s_nop 0
	global_load_lds_dwordx4 v[206:207], off
	s_waitcnt vmcnt(8)
	s_waitcnt lgkmcnt(0)
	s_barrier
	s_setprio 1
	s_waitcnt lgkmcnt(0)
	v_mfma_f32_16x16x32_bf16 v[124:127], v[128:131], v[160:163], v[124:127]
	v_mfma_f32_16x16x32_bf16 v[120:123], v[136:139], v[160:163], v[120:123]
	v_mfma_f32_16x16x32_bf16 v[108:111], v[128:131], v[168:171], v[108:111]
	v_mfma_f32_16x16x32_bf16 v[104:107], v[136:139], v[168:171], v[104:107]
	v_mfma_f32_16x16x32_bf16 v[96:99], v[128:131], v[176:179], v[96:99]
	v_mfma_f32_16x16x32_bf16 v[88:91], v[136:139], v[176:179], v[88:91]
	v_mfma_f32_16x16x32_bf16 v[80:83], v[128:131], v[184:187], v[80:83]
	v_mfma_f32_16x16x32_bf16 v[72:75], v[136:139], v[184:187], v[72:75]
	v_mfma_f32_16x16x32_bf16 v[124:127], v[132:135], v[164:167], v[124:127]
	v_mfma_f32_16x16x32_bf16 v[120:123], v[140:143], v[164:167], v[120:123]
	v_mfma_f32_16x16x32_bf16 v[108:111], v[132:135], v[172:175], v[108:111]
	v_mfma_f32_16x16x32_bf16 v[104:107], v[140:143], v[172:175], v[104:107]
	v_mfma_f32_16x16x32_bf16 v[96:99], v[132:135], v[180:183], v[96:99]
	v_mfma_f32_16x16x32_bf16 v[88:91], v[140:143], v[180:183], v[88:91]
	v_mfma_f32_16x16x32_bf16 v[80:83], v[132:135], v[202:205], v[80:83]
	v_mfma_f32_16x16x32_bf16 v[72:75], v[140:143], v[202:205], v[72:75]
	v_mfma_f32_16x16x32_bf16 v[116:119], v[144:147], v[160:163], v[116:119]
	v_mfma_f32_16x16x32_bf16 v[112:115], v[152:155], v[160:163], v[112:115]
	v_mfma_f32_16x16x32_bf16 v[100:103], v[144:147], v[168:171], v[100:103]
	v_mfma_f32_16x16x32_bf16 v[92:95], v[152:155], v[168:171], v[92:95]
	v_mfma_f32_16x16x32_bf16 v[84:87], v[144:147], v[176:179], v[84:87]
	v_mfma_f32_16x16x32_bf16 v[76:79], v[152:155], v[176:179], v[76:79]
	v_mfma_f32_16x16x32_bf16 v[68:71], v[144:147], v[184:187], v[68:71]
	v_mfma_f32_16x16x32_bf16 v[64:67], v[152:155], v[184:187], v[64:67]
	v_mfma_f32_16x16x32_bf16 v[116:119], v[148:151], v[164:167], v[116:119]
	v_mfma_f32_16x16x32_bf16 v[112:115], v[156:159], v[164:167], v[112:115]
	v_mfma_f32_16x16x32_bf16 v[100:103], v[148:151], v[172:175], v[100:103]
	v_mfma_f32_16x16x32_bf16 v[92:95], v[156:159], v[172:175], v[92:95]
	v_mfma_f32_16x16x32_bf16 v[84:87], v[148:151], v[180:183], v[84:87]
	v_mfma_f32_16x16x32_bf16 v[76:79], v[156:159], v[180:183], v[76:79]
	v_mfma_f32_16x16x32_bf16 v[68:71], v[148:151], v[202:205], v[68:71]
	v_mfma_f32_16x16x32_bf16 v[64:67], v[156:159], v[202:205], v[64:67]
	s_setprio 0
	s_barrier
	s_add_i32 s10, s12, s4
	v_lshl_add_u64 v[206:207], s[60:61], 0, v[192:193]
	s_mov_b32 m0, s10
	ds_read_b128 v[160:163], v220 offset:16384
	ds_read_b128 v[164:167], v220 offset:17408
	ds_read_b128 v[168:171], v220 offset:18432
	ds_read_b128 v[172:175], v220 offset:19456
	ds_read_b128 v[176:179], v220 offset:20480
	ds_read_b128 v[180:183], v220 offset:21504
	ds_read_b128 v[184:187], v220 offset:22528
	ds_read_b128 v[202:205], v220 offset:23552
	global_load_lds_dwordx4 v[206:207], off
	s_add_i32 m0, s10, 0x2000
	s_add_u32 s10, s60, 0x100000
	v_lshl_add_u64 v[208:209], s[60:61], 0, v[188:189]
	s_addc_u32 s11, s61, 0
	s_add_i32 s12, s13, s4
	global_load_lds_dwordx4 v[208:209], off
	v_lshl_add_u64 v[210:211], s[10:11], 0, v[192:193]
	s_mov_b32 m0, s12
	v_lshl_add_u64 v[212:213], s[64:65], 0, v[190:191]
	global_load_lds_dwordx4 v[210:211], off
	v_lshl_add_u64 v[210:211], s[10:11], 0, v[188:189]
	s_add_i32 m0, s12, 0x2000
	s_nop 0
	global_load_lds_dwordx4 v[210:211], off
	v_lshl_add_u64 v[210:211], s[64:65], 0, v[196:197]
	s_mov_b32 m0, s7
	s_nop 0
	global_load_lds_dwordx4 v[210:211], off
	s_mov_b32 m0, s66
	s_nop 0
	global_load_lds_dwordx4 v[212:213], off
	s_waitcnt vmcnt(8)
	s_waitcnt lgkmcnt(0)
	s_barrier
; #define PG8_STAGE(bufoff, gbase, voff) do { _Pragma("unroll") for (int _i = 0; _i < 2; ++_i) \
;         __builtin_amdgcn_global_load_lds((const unsigned*)((const char*)(gbase) + (voff)[_i]), (PG8_LAS unsigned*)(lds + (bufoff) + ldsw + _i * 8192), 16, 0, 0); } while (0)
; #define PG8_LDA(dst, b, h) do { _Pragma("unroll") for (int m = 0; m < 4; ++m) _Pragma("unroll") for (int k = 0; k < 2; ++k) dst[m][k] = *(const PG8_LAS bf16x8*)(lds + PG8_SA(b, h) + aoff + m * 2048 + k * 1024); } while (0)
; #define PG8_LDB(dst, b, h) do { _Pragma("unroll") for (int n = 0; n < 2; ++n) _Pragma("unroll") for (int k = 0; k < 2; ++k) dst[n][k] = *(const PG8_LAS bf16x8*)(lds + PG8_SB(b, h) + boff + n * 2048 + k * 1024); } while (0)
; #define PG8_MMA(ai, bj, At, Bt) do { __builtin_amdgcn_s_setprio(1); _Pragma("unroll") for (int m = 0; m < 4; ++m) _Pragma("unroll") for (int n = 0; n < 2; ++n) _Pragma("unroll") for (int k = 0; k < 2; ++k) \
;         acc[ai][bj][m][n] = __builtin_amdgcn_mfma_f32_16x16x32_bf16(Bt[n][k], At[m][k], acc[ai][bj][m][n], 0, 0, 0); __builtin_amdgcn_s_setprio(0); } while (0)
; #define PG8_WAIT_V(n) asm volatile("s_waitcnt vmcnt(" #n ")" ::: "memory")
; #define PG8_WAIT_L(n) asm volatile("s_waitcnt lgkmcnt(" #n ")" ::: "memory")
; #define PG8_BAR __builtin_amdgcn_s_barrier()
; #define PG8_SCHED __builtin_amdgcn_sched_barrier(0)
; template <class Epi, class Sched, bool ALIGN_EPI = false, bool SP2 = false>
; __device__ __forceinline__ void gemm_phase(PG8_LAS unsigned char* lds, const Gemm g, const Sched& S, const Epi& E, const int tid) {
;     ...
;             PG8_WAIT_V(8); PG8_WAIT_L(0); PG8_BAR; PG8_MMA(1, 0, At, B0); PG8_MMA(1, 1, At, B1); PG8_BAR; PG8_SCHED;
;             PG8_LDB(B0, 1, 0); PG8_LDB(B1, 1, 1); PG8_SCHED; PG8_LDA(At, 1, 0); PG8_STAGE(PG8_SA(0, 1), a2 + hstep, voffA);
;             PG8_WAIT_V(8); PG8_WAIT_L(0); PG8_BAR; PG8_MMA(0, 0, At, B0); PG8_MMA(0, 1, At, B1); PG8_BAR; PG8_SCHED;
	s_setprio 1
	s_waitcnt lgkmcnt(0)
	v_mfma_f32_16x16x32_bf16 v[60:63], v[128:131], v[160:163], v[60:63]
	v_mfma_f32_16x16x32_bf16 v[56:59], v[136:139], v[160:163], v[56:59]
	v_mfma_f32_16x16x32_bf16 v[48:51], v[128:131], v[168:171], v[48:51]
	v_mfma_f32_16x16x32_bf16 v[40:43], v[136:139], v[168:171], v[40:43]
	v_mfma_f32_16x16x32_bf16 v[32:35], v[128:131], v[176:179], v[32:35]
	v_mfma_f32_16x16x32_bf16 v[24:27], v[136:139], v[176:179], v[24:27]
	v_mfma_f32_16x16x32_bf16 v[16:19], v[128:131], v[184:187], v[16:19]
	v_mfma_f32_16x16x32_bf16 v[8:11], v[136:139], v[184:187], v[8:11]
	v_mfma_f32_16x16x32_bf16 v[60:63], v[132:135], v[164:167], v[60:63]
	v_mfma_f32_16x16x32_bf16 v[56:59], v[140:143], v[164:167], v[56:59]
	v_mfma_f32_16x16x32_bf16 v[48:51], v[132:135], v[172:175], v[48:51]
	v_mfma_f32_16x16x32_bf16 v[40:43], v[140:143], v[172:175], v[40:43]
	v_mfma_f32_16x16x32_bf16 v[32:35], v[132:135], v[180:183], v[32:35]
	v_mfma_f32_16x16x32_bf16 v[24:27], v[140:143], v[180:183], v[24:27]
	v_mfma_f32_16x16x32_bf16 v[16:19], v[132:135], v[202:205], v[16:19]
	v_mfma_f32_16x16x32_bf16 v[8:11], v[140:143], v[202:205], v[8:11]
	v_mfma_f32_16x16x32_bf16 v[52:55], v[144:147], v[160:163], v[52:55]
	v_mfma_f32_16x16x32_bf16 v[44:47], v[152:155], v[160:163], v[44:47]
	v_mfma_f32_16x16x32_bf16 v[36:39], v[144:147], v[168:171], v[36:39]
	v_mfma_f32_16x16x32_bf16 v[28:31], v[152:155], v[168:171], v[28:31]
	v_mfma_f32_16x16x32_bf16 v[20:23], v[144:147], v[176:179], v[20:23]
	v_mfma_f32_16x16x32_bf16 v[12:15], v[152:155], v[176:179], v[12:15]
	v_mfma_f32_16x16x32_bf16 v[4:7], v[144:147], v[184:187], v[4:7]
	v_mfma_f32_16x16x32_bf16 v[0:3], v[152:155], v[184:187], v[0:3]
	v_mfma_f32_16x16x32_bf16 v[52:55], v[148:151], v[164:167], v[52:55]
	v_mfma_f32_16x16x32_bf16 v[44:47], v[156:159], v[164:167], v[44:47]
	v_mfma_f32_16x16x32_bf16 v[36:39], v[148:151], v[172:175], v[36:39]
	v_mfma_f32_16x16x32_bf16 v[28:31], v[156:159], v[172:175], v[28:31]
	v_mfma_f32_16x16x32_bf16 v[20:23], v[148:151], v[180:183], v[20:23]
	v_mfma_f32_16x16x32_bf16 v[12:15], v[156:159], v[180:183], v[12:15]
	v_mfma_f32_16x16x32_bf16 v[4:7], v[148:151], v[202:205], v[4:7]
	v_mfma_f32_16x16x32_bf16 v[0:3], v[156:159], v[202:205], v[0:3]
	s_setprio 0
	s_barrier
	s_add_i32 s12, 0, 0x18000
	s_add_i32 s13, 0, 0x1c000
	v_add_u32_e32 v140, s12, v218
	v_add_u32_e32 v156, s13, v218
	ds_read_b128 v[128:131], v140
	ds_read_b128 v[132:135], v140 offset:1024
	ds_read_b128 v[136:139], v140 offset:2048
	ds_read_b128 v[140:143], v140 offset:3072
	ds_read_b128 v[144:147], v156
	ds_read_b128 v[148:151], v156 offset:1024
	ds_read_b128 v[152:155], v156 offset:2048
	ds_read_b128 v[156:159], v156 offset:3072
	s_add_u32 s10, s64, 0x100000
	s_addc_u32 s11, s65, 0
	s_mov_b32 m0, s67
	v_lshl_add_u64 v[214:215], s[10:11], 0, v[196:197]
	ds_read_b128 v[160:163], v220 offset:32768
	ds_read_b128 v[164:167], v220 offset:33792
	ds_read_b128 v[168:171], v220 offset:34816
	ds_read_b128 v[172:175], v220 offset:35840
	ds_read_b128 v[176:179], v220 offset:36864
	ds_read_b128 v[180:183], v220 offset:37888
	ds_read_b128 v[184:187], v220 offset:38912
	ds_read_b128 v[202:205], v220 offset:39936
	global_load_lds_dwordx4 v[214:215], off
	v_lshl_add_u64 v[214:215], s[10:11], 0, v[190:191]
	s_mov_b32 m0, s76
	s_nop 0
	global_load_lds_dwordx4 v[214:215], off
	s_waitcnt vmcnt(8)
	s_waitcnt lgkmcnt(0)
	s_barrier
	s_setprio 1
	s_waitcnt lgkmcnt(0)
	v_mfma_f32_16x16x32_bf16 v[124:127], v[128:131], v[160:163], v[124:127]
	v_mfma_f32_16x16x32_bf16 v[120:123], v[136:139], v[160:163], v[120:123]
	v_mfma_f32_16x16x32_bf16 v[108:111], v[128:131], v[168:171], v[108:111]
	v_mfma_f32_16x16x32_bf16 v[104:107], v[136:139], v[168:171], v[104:107]
	v_mfma_f32_16x16x32_bf16 v[96:99], v[128:131], v[176:179], v[96:99]
	v_mfma_f32_16x16x32_bf16 v[88:91], v[136:139], v[176:179], v[88:91]
	v_mfma_f32_16x16x32_bf16 v[80:83], v[128:131], v[184:187], v[80:83]
	v_mfma_f32_16x16x32_bf16 v[72:75], v[136:139], v[184:187], v[72:75]
	v_mfma_f32_16x16x32_bf16 v[124:127], v[132:135], v[164:167], v[124:127]
	v_mfma_f32_16x16x32_bf16 v[120:123], v[140:143], v[164:167], v[120:123]
	v_mfma_f32_16x16x32_bf16 v[108:111], v[132:135], v[172:175], v[108:111]
	v_mfma_f32_16x16x32_bf16 v[104:107], v[140:143], v[172:175], v[104:107]
	v_mfma_f32_16x16x32_bf16 v[96:99], v[132:135], v[180:183], v[96:99]
	v_mfma_f32_16x16x32_bf16 v[88:91], v[140:143], v[180:183], v[88:91]
	v_mfma_f32_16x16x32_bf16 v[80:83], v[132:135], v[202:205], v[80:83]
	v_mfma_f32_16x16x32_bf16 v[72:75], v[140:143], v[202:205], v[72:75]
	v_mfma_f32_16x16x32_bf16 v[116:119], v[144:147], v[160:163], v[116:119]
	v_mfma_f32_16x16x32_bf16 v[112:115], v[152:155], v[160:163], v[112:115]
	v_mfma_f32_16x16x32_bf16 v[100:103], v[144:147], v[168:171], v[100:103]
	v_mfma_f32_16x16x32_bf16 v[92:95], v[152:155], v[168:171], v[92:95]
	v_mfma_f32_16x16x32_bf16 v[84:87], v[144:147], v[176:179], v[84:87]
	v_mfma_f32_16x16x32_bf16 v[76:79], v[152:155], v[176:179], v[76:79]
	v_mfma_f32_16x16x32_bf16 v[68:71], v[144:147], v[184:187], v[68:71]
	v_mfma_f32_16x16x32_bf16 v[64:67], v[152:155], v[184:187], v[64:67]
	v_mfma_f32_16x16x32_bf16 v[116:119], v[148:151], v[164:167], v[116:119]
	v_mfma_f32_16x16x32_bf16 v[112:115], v[156:159], v[164:167], v[112:115]
	v_mfma_f32_16x16x32_bf16 v[100:103], v[148:151], v[172:175], v[100:103]
	v_mfma_f32_16x16x32_bf16 v[92:95], v[156:159], v[172:175], v[92:95]
	v_mfma_f32_16x16x32_bf16 v[84:87], v[148:151], v[180:183], v[84:87]
	v_mfma_f32_16x16x32_bf16 v[76:79], v[156:159], v[180:183], v[76:79]
	v_mfma_f32_16x16x32_bf16 v[68:71], v[148:151], v[202:205], v[68:71]
	v_mfma_f32_16x16x32_bf16 v[64:67], v[156:159], v[202:205], v[64:67]
	s_setprio 0
	s_barrier
; #define PG8_STAGE(bufoff, gbase, voff) do { _Pragma("unroll") for (int _i = 0; _i < 2; ++_i) \
;         __builtin_amdgcn_global_load_lds((const unsigned*)((const char*)(gbase) + (voff)[_i]), (PG8_LAS unsigned*)(lds + (bufoff) + ldsw + _i * 8192), 16, 0, 0); } while (0)
; #define PG8_LDA(dst, b, h) do { _Pragma("unroll") for (int m = 0; m < 4; ++m) _Pragma("unroll") for (int k = 0; k < 2; ++k) dst[m][k] = *(const PG8_LAS bf16x8*)(lds + PG8_SA(b, h) + aoff + m * 2048 + k * 1024); } while (0)
; #define PG8_MMA(ai, bj, At, Bt) do { __builtin_amdgcn_s_setprio(1); _Pragma("unroll") for (int m = 0; m < 4; ++m) _Pragma("unroll") for (int n = 0; n < 2; ++n) _Pragma("unroll") for (int k = 0; k < 2; ++k) \
;         acc[ai][bj][m][n] = __builtin_amdgcn_mfma_f32_16x16x32_bf16(Bt[n][k], At[m][k], acc[ai][bj][m][n], 0, 0, 0); __builtin_amdgcn_s_setprio(0); } while (0)
; #define PG8_WAIT_V(n) asm volatile("s_waitcnt vmcnt(" #n ")" ::: "memory")
; #define PG8_WAIT_L(n) asm volatile("s_waitcnt lgkmcnt(" #n ")" ::: "memory")
; #define PG8_BAR __builtin_amdgcn_s_barrier()
; #define PG8_SCHED __builtin_amdgcn_sched_barrier(0)
; template <class Epi, class Sched, bool ALIGN_EPI = false, bool SP2 = false>
; __device__ __forceinline__ void gemm_phase(PG8_LAS unsigned char* lds, const Gemm g, const Sched& S, const Epi& E, const int tid) {
;     ...
;             PG8_LDA(At, 1, 1); PG8_STAGE(PG8_SB(1, 0), b3, voffB); PG8_STAGE(PG8_SB(1, 1), b3 + hstep, voffB); PG8_STAGE(PG8_SA(1, 0), a3, voffA);
;             PG8_WAIT_V(8); PG8_WAIT_L(0); PG8_BAR; PG8_MMA(1, 0, At, B0); PG8_MMA(1, 1, At, B1); PG8_BAR; PG8_SCHED;
;     ...
;         if constexpr (ALIGN_EPI) { if (wr == 0) PG8_BAR; }
	s_add_i32 s10, s12, s4
	v_lshl_add_u64 v[206:207], v[206:207], 0, s[22:23]
	s_mov_b32 m0, s10
	ds_read_b128 v[160:163], v220 offset:49152
	ds_read_b128 v[164:167], v220 offset:50176
	ds_read_b128 v[168:171], v220 offset:51200
	ds_read_b128 v[172:175], v220 offset:52224
	ds_read_b128 v[176:179], v220 offset:53248
	ds_read_b128 v[180:183], v220 offset:54272
	ds_read_b128 v[184:187], v220 offset:55296
	ds_read_b128 v[202:205], v220 offset:56320
	global_load_lds_dwordx4 v[206:207], off
	s_add_i32 m0, s10, 0x2000
	s_add_u32 s10, s60, 0x100080
	v_lshl_add_u64 v[206:207], v[208:209], 0, s[22:23]
	s_addc_u32 s11, s61, 0
	s_add_i32 s12, s13, s4
	global_load_lds_dwordx4 v[206:207], off
	v_lshl_add_u64 v[206:207], s[10:11], 0, v[192:193]
	s_mov_b32 m0, s12
	s_nop 0
	global_load_lds_dwordx4 v[206:207], off
	v_lshl_add_u64 v[206:207], s[10:11], 0, v[188:189]
	s_add_i32 m0, s12, 0x2000
	s_nop 0
	global_load_lds_dwordx4 v[206:207], off
	v_lshl_add_u64 v[206:207], v[210:211], 0, s[22:23]
	s_mov_b32 m0, s77
	s_nop 0
	global_load_lds_dwordx4 v[206:207], off
	v_lshl_add_u64 v[206:207], v[212:213], 0, s[22:23]
	s_mov_b32 m0, s82
	s_nop 0
	global_load_lds_dwordx4 v[206:207], off
	s_waitcnt vmcnt(8)
	s_waitcnt lgkmcnt(0)
	s_barrier
	s_setprio 1
	s_waitcnt lgkmcnt(0)
	v_mfma_f32_16x16x32_bf16 v[60:63], v[128:131], v[160:163], v[60:63]
	v_mfma_f32_16x16x32_bf16 v[56:59], v[136:139], v[160:163], v[56:59]
	v_mfma_f32_16x16x32_bf16 v[48:51], v[128:131], v[168:171], v[48:51]
	v_mfma_f32_16x16x32_bf16 v[40:43], v[136:139], v[168:171], v[40:43]
	v_mfma_f32_16x16x32_bf16 v[32:35], v[128:131], v[176:179], v[32:35]
	v_mfma_f32_16x16x32_bf16 v[24:27], v[136:139], v[176:179], v[24:27]
	v_mfma_f32_16x16x32_bf16 v[16:19], v[128:131], v[184:187], v[16:19]
	v_mfma_f32_16x16x32_bf16 v[8:11], v[136:139], v[184:187], v[8:11]
	v_mfma_f32_16x16x32_bf16 v[60:63], v[132:135], v[164:167], v[60:63]
	v_mfma_f32_16x16x32_bf16 v[56:59], v[140:143], v[164:167], v[56:59]
	v_mfma_f32_16x16x32_bf16 v[48:51], v[132:135], v[172:175], v[48:51]
	v_mfma_f32_16x16x32_bf16 v[40:43], v[140:143], v[172:175], v[40:43]
	v_mfma_f32_16x16x32_bf16 v[32:35], v[132:135], v[180:183], v[32:35]
	v_mfma_f32_16x16x32_bf16 v[24:27], v[140:143], v[180:183], v[24:27]
	v_mfma_f32_16x16x32_bf16 v[16:19], v[132:135], v[202:205], v[16:19]
	v_mfma_f32_16x16x32_bf16 v[8:11], v[140:143], v[202:205], v[8:11]
	v_mfma_f32_16x16x32_bf16 v[52:55], v[144:147], v[160:163], v[52:55]
	v_mfma_f32_16x16x32_bf16 v[44:47], v[152:155], v[160:163], v[44:47]
	v_mfma_f32_16x16x32_bf16 v[36:39], v[144:147], v[168:171], v[36:39]
	v_mfma_f32_16x16x32_bf16 v[28:31], v[152:155], v[168:171], v[28:31]
	v_mfma_f32_16x16x32_bf16 v[20:23], v[144:147], v[176:179], v[20:23]
	v_mfma_f32_16x16x32_bf16 v[12:15], v[152:155], v[176:179], v[12:15]
	v_mfma_f32_16x16x32_bf16 v[4:7], v[144:147], v[184:187], v[4:7]
	v_mfma_f32_16x16x32_bf16 v[0:3], v[152:155], v[184:187], v[0:3]
	v_mfma_f32_16x16x32_bf16 v[52:55], v[148:151], v[164:167], v[52:55]
	v_mfma_f32_16x16x32_bf16 v[44:47], v[156:159], v[164:167], v[44:47]
	v_mfma_f32_16x16x32_bf16 v[36:39], v[148:151], v[172:175], v[36:39]
	v_mfma_f32_16x16x32_bf16 v[28:31], v[156:159], v[172:175], v[28:31]
	v_mfma_f32_16x16x32_bf16 v[20:23], v[148:151], v[180:183], v[20:23]
	v_mfma_f32_16x16x32_bf16 v[12:15], v[156:159], v[180:183], v[12:15]
	v_mfma_f32_16x16x32_bf16 v[4:7], v[148:151], v[202:205], v[4:7]
	v_mfma_f32_16x16x32_bf16 v[0:3], v[156:159], v[202:205], v[0:3]
	s_setprio 0
	s_barrier
	s_add_i32 s9, s9, 2
	s_add_u32 s58, s58, 0x100
	s_addc_u32 s59, s59, 0
	s_add_u32 s87, s87, 0x100
	s_addc_u32 s8, s8, 0
	s_cmp_gt_u32 s9, 61
	s_cbranch_scc0 .LBB0_236
	s_and_b64 vcc, exec, s[40:41]
	s_cbranch_vccz .LBB0_239
	s_barrier

; #define PG8_STAGE(bufoff, gbase, voff) do { _Pragma("unroll") for (int _i = 0; _i < 2; ++_i) \
;         __builtin_amdgcn_global_load_lds((const unsigned*)((const char*)(gbase) + (voff)[_i]), (PG8_LAS unsigned*)(lds + (bufoff) + ldsw + _i * 8192), 16, 0, 0); } while (0)
; #define PG8_LDA(dst, b, h) do { _Pragma("unroll") for (int m = 0; m < 4; ++m) _Pragma("unroll") for (int k = 0; k < 2; ++k) dst[m][k] = *(const PG8_LAS bf16x8*)(lds + PG8_SA(b, h) + aoff + m * 2048 + k * 1024); } while (0)
; #define PG8_LDB(dst, b, h) do { _Pragma("unroll") for (int n = 0; n < 2; ++n) _Pragma("unroll") for (int k = 0; k < 2; ++k) dst[n][k] = *(const PG8_LAS bf16x8*)(lds + PG8_SB(b, h) + boff + n * 2048 + k * 1024); } while (0)
; #define PG8_MMA(ai, bj, At, Bt) do { __builtin_amdgcn_s_setprio(1); _Pragma("unroll") for (int m = 0; m < 4; ++m) _Pragma("unroll") for (int n = 0; n < 2; ++n) _Pragma("unroll") for (int k = 0; k < 2; ++k) \
;         acc[ai][bj][m][n] = __builtin_amdgcn_mfma_f32_16x16x32_bf16(Bt[n][k], At[m][k], acc[ai][bj][m][n], 0, 0, 0); __builtin_amdgcn_s_setprio(0); } while (0)
; #define PG8_WAIT_V(n) asm volatile("s_waitcnt vmcnt(" #n ")" ::: "memory")
; #define PG8_WAIT_L(n) asm volatile("s_waitcnt lgkmcnt(" #n ")" ::: "memory")
; #define PG8_BAR __builtin_amdgcn_s_barrier()
; #define PG8_SCHED __builtin_amdgcn_sched_barrier(0)
; template <class Epi, class Sched, bool ALIGN_EPI = false, bool SP2 = false>
; __device__ __forceinline__ void gemm_phase(PG8_LAS unsigned char* lds, const Gemm g, const Sched& S, const Epi& E, const int tid) {
;     ...
;             PG8_LDB(B0, 0, 0); PG8_LDB(B1, 0, 1); PG8_SCHED; PG8_LDA(At, 0, 0); PG8_STAGE(PG8_SA(1, 1), a1 + hstep, voffA);
;             PG8_WAIT_V(8); PG8_WAIT_L(0); PG8_BAR; PG8_MMA(0, 0, At, B0); PG8_MMA(0, 1, At, B1); PG8_BAR; PG8_SCHED;
;             PG8_LDA(At, 0, 1); PG8_STAGE(PG8_SB(0, 0), b2, voffB); PG8_STAGE(PG8_SB(0, 1), b2 + hstep, voffB); PG8_STAGE(PG8_SA(0, 0), a2, voffA);
;             PG8_WAIT_V(8); PG8_WAIT_L(0); PG8_BAR; PG8_MMA(1, 0, At, B0); PG8_MMA(1, 1, At, B1); PG8_BAR; PG8_SCHED;
.LBB0_270:
	s_add_u32 s10, s64, 0xfffc0080
	s_addc_u32 s11, s65, -1
	s_add_i32 s12, 0, 0x10000
	s_cmp_eq_u32 s9, 12
	s_cselect_b32 s85, s1, s11
	s_cselect_b32 s84, s57, s10
	v_add_u32_e32 v142, s12, v144
	s_cselect_b32 s67, s31, s8
	s_cselect_b32 s66, s95, s96
	s_add_i32 s13, 0, 0x14000
	ds_read_b128 v[138:141], v142
	ds_read_b128 v[148:151], v142 offset:1024
	ds_read_b128 v[152:155], v142 offset:2048
	ds_read_b128 v[156:159], v142 offset:3072
	v_add_u32_e32 v142, s13, v144
	ds_read_b128 v[160:163], v142
	ds_read_b128 v[164:167], v142 offset:1024
	ds_read_b128 v[168:171], v142 offset:2048
	ds_read_b128 v[172:175], v142 offset:3072
	v_lshl_add_u64 v[212:213], s[64:65], 0, v[134:135]
	s_add_i32 m0, s77, 0xc000
	ds_read_b128 v[176:179], v147
	ds_read_b128 v[180:183], v147 offset:1024
	ds_read_b128 v[184:187], v147 offset:2048
	ds_read_b128 v[188:191], v147 offset:3072
	ds_read_b128 v[196:199], v147 offset:4096
	ds_read_b128 v[200:203], v147 offset:5120
	ds_read_b128 v[204:207], v147 offset:6144
	ds_read_b128 v[208:211], v147 offset:7168
	global_load_lds_dwordx4 v[212:213], off
	v_lshl_add_u64 v[212:213], s[64:65], 0, v[136:137]
	s_add_i32 m0, s77, 0xe000
	s_nop 0
	global_load_lds_dwordx4 v[212:213], off
	s_waitcnt vmcnt(8)
	s_waitcnt lgkmcnt(0)
	s_barrier
	s_setprio 1
	s_waitcnt lgkmcnt(0)
	v_mfma_f32_16x16x32_bf16 v[124:127], v[138:141], v[176:179], v[124:127]
	v_mfma_f32_16x16x32_bf16 v[120:123], v[152:155], v[176:179], v[120:123]
	v_mfma_f32_16x16x32_bf16 v[108:111], v[138:141], v[184:187], v[108:111]
	v_mfma_f32_16x16x32_bf16 v[104:107], v[152:155], v[184:187], v[104:107]
	v_mfma_f32_16x16x32_bf16 v[92:95], v[138:141], v[196:199], v[92:95]
	v_mfma_f32_16x16x32_bf16 v[88:91], v[152:155], v[196:199], v[88:91]
	v_mfma_f32_16x16x32_bf16 v[76:79], v[138:141], v[204:207], v[76:79]
	v_mfma_f32_16x16x32_bf16 v[72:75], v[152:155], v[204:207], v[72:75]
	v_mfma_f32_16x16x32_bf16 v[124:127], v[148:151], v[180:183], v[124:127]
	v_mfma_f32_16x16x32_bf16 v[120:123], v[156:159], v[180:183], v[120:123]
	v_mfma_f32_16x16x32_bf16 v[108:111], v[148:151], v[188:191], v[108:111]
	v_mfma_f32_16x16x32_bf16 v[104:107], v[156:159], v[188:191], v[104:107]
	v_mfma_f32_16x16x32_bf16 v[92:95], v[148:151], v[200:203], v[92:95]
	v_mfma_f32_16x16x32_bf16 v[88:91], v[156:159], v[200:203], v[88:91]
	v_mfma_f32_16x16x32_bf16 v[76:79], v[148:151], v[208:211], v[76:79]
	v_mfma_f32_16x16x32_bf16 v[72:75], v[156:159], v[208:211], v[72:75]
	v_mfma_f32_16x16x32_bf16 v[116:119], v[160:163], v[176:179], v[116:119]
	v_mfma_f32_16x16x32_bf16 v[112:115], v[168:171], v[176:179], v[112:115]
	v_mfma_f32_16x16x32_bf16 v[100:103], v[160:163], v[184:187], v[100:103]
	v_mfma_f32_16x16x32_bf16 v[96:99], v[168:171], v[184:187], v[96:99]
	v_mfma_f32_16x16x32_bf16 v[84:87], v[160:163], v[196:199], v[84:87]
	v_mfma_f32_16x16x32_bf16 v[80:83], v[168:171], v[196:199], v[80:83]
	v_mfma_f32_16x16x32_bf16 v[68:71], v[160:163], v[204:207], v[68:71]
	v_mfma_f32_16x16x32_bf16 v[64:67], v[168:171], v[204:207], v[64:67]
	v_mfma_f32_16x16x32_bf16 v[116:119], v[164:167], v[180:183], v[116:119]
	v_mfma_f32_16x16x32_bf16 v[112:115], v[172:175], v[180:183], v[112:115]
	v_mfma_f32_16x16x32_bf16 v[100:103], v[164:167], v[188:191], v[100:103]
	v_mfma_f32_16x16x32_bf16 v[96:99], v[172:175], v[188:191], v[96:99]
	v_mfma_f32_16x16x32_bf16 v[84:87], v[164:167], v[200:203], v[84:87]
	v_mfma_f32_16x16x32_bf16 v[80:83], v[172:175], v[200:203], v[80:83]
	v_mfma_f32_16x16x32_bf16 v[68:71], v[164:167], v[208:211], v[68:71]
	v_mfma_f32_16x16x32_bf16 v[64:67], v[172:175], v[208:211], v[64:67]
	s_setprio 0
	s_barrier
	s_add_i32 s10, s12, s6
	v_lshl_add_u64 v[212:213], s[66:67], 0, v[192:193]
	s_mov_b32 m0, s10
	ds_read_b128 v[176:179], v147 offset:16384
	ds_read_b128 v[180:183], v147 offset:17408
	ds_read_b128 v[184:187], v147 offset:18432
	ds_read_b128 v[188:191], v147 offset:19456
	ds_read_b128 v[196:199], v147 offset:20480
	ds_read_b128 v[200:203], v147 offset:21504
	ds_read_b128 v[204:207], v147 offset:22528
	ds_read_b128 v[208:211], v147 offset:23552
	global_load_lds_dwordx4 v[212:213], off
	s_add_i32 m0, s10, 0x2000
	s_add_u32 s10, s66, 0x40000
	v_lshl_add_u64 v[214:215], s[66:67], 0, v[132:133]
	s_addc_u32 s11, s67, 0
	s_add_i32 s12, s13, s6
	global_load_lds_dwordx4 v[214:215], off
	v_lshl_add_u64 v[216:217], s[10:11], 0, v[192:193]
	s_mov_b32 m0, s12
	v_lshl_add_u64 v[218:219], s[84:85], 0, v[130:131]
	global_load_lds_dwordx4 v[216:217], off
	v_lshl_add_u64 v[216:217], s[10:11], 0, v[132:133]
	s_add_i32 m0, s12, 0x2000
	s_nop 0
	global_load_lds_dwordx4 v[216:217], off
	v_lshl_add_u64 v[216:217], s[84:85], 0, v[128:129]
	s_mov_b32 m0, s77
	s_nop 0
	global_load_lds_dwordx4 v[216:217], off
	s_mov_b32 m0, s86
	s_nop 0
	global_load_lds_dwordx4 v[218:219], off
	s_waitcnt vmcnt(8)
	s_waitcnt lgkmcnt(0)
	s_barrier
; #define PG8_STAGE(bufoff, gbase, voff) do { _Pragma("unroll") for (int _i = 0; _i < 2; ++_i) \
;         __builtin_amdgcn_global_load_lds((const unsigned*)((const char*)(gbase) + (voff)[_i]), (PG8_LAS unsigned*)(lds + (bufoff) + ldsw + _i * 8192), 16, 0, 0); } while (0)
; #define PG8_LDA(dst, b, h) do { _Pragma("unroll") for (int m = 0; m < 4; ++m) _Pragma("unroll") for (int k = 0; k < 2; ++k) dst[m][k] = *(const PG8_LAS bf16x8*)(lds + PG8_SA(b, h) + aoff + m * 2048 + k * 1024); } while (0)
; #define PG8_LDB(dst, b, h) do { _Pragma("unroll") for (int n = 0; n < 2; ++n) _Pragma("unroll") for (int k = 0; k < 2; ++k) dst[n][k] = *(const PG8_LAS bf16x8*)(lds + PG8_SB(b, h) + boff + n * 2048 + k * 1024); } while (0)
; #define PG8_MMA(ai, bj, At, Bt) do { __builtin_amdgcn_s_setprio(1); _Pragma("unroll") for (int m = 0; m < 4; ++m) _Pragma("unroll") for (int n = 0; n < 2; ++n) _Pragma("unroll") for (int k = 0; k < 2; ++k) \
;         acc[ai][bj][m][n] = __builtin_amdgcn_mfma_f32_16x16x32_bf16(Bt[n][k], At[m][k], acc[ai][bj][m][n], 0, 0, 0); __builtin_amdgcn_s_setprio(0); } while (0)
; #define PG8_WAIT_V(n) asm volatile("s_waitcnt vmcnt(" #n ")" ::: "memory")
; #define PG8_WAIT_L(n) asm volatile("s_waitcnt lgkmcnt(" #n ")" ::: "memory")
; #define PG8_BAR __builtin_amdgcn_s_barrier()
; #define PG8_SCHED __builtin_amdgcn_sched_barrier(0)
; template <class Epi, class Sched, bool ALIGN_EPI = false, bool SP2 = false>
; __device__ __forceinline__ void gemm_phase(PG8_LAS unsigned char* lds, const Gemm g, const Sched& S, const Epi& E, const int tid) {
;     ...
;             PG8_WAIT_V(8); PG8_WAIT_L(0); PG8_BAR; PG8_MMA(1, 0, At, B0); PG8_MMA(1, 1, At, B1); PG8_BAR; PG8_SCHED;
;             PG8_LDB(B0, 1, 0); PG8_LDB(B1, 1, 1); PG8_SCHED; PG8_LDA(At, 1, 0); PG8_STAGE(PG8_SA(0, 1), a2 + hstep, voffA);
;             PG8_WAIT_V(8); PG8_WAIT_L(0); PG8_BAR; PG8_MMA(0, 0, At, B0); PG8_MMA(0, 1, At, B1); PG8_BAR; PG8_SCHED;
	s_setprio 1
	s_waitcnt lgkmcnt(0)
	v_mfma_f32_16x16x32_bf16 v[60:63], v[138:141], v[176:179], v[60:63]
	v_mfma_f32_16x16x32_bf16 v[56:59], v[152:155], v[176:179], v[56:59]
	v_mfma_f32_16x16x32_bf16 v[44:47], v[138:141], v[184:187], v[44:47]
	v_mfma_f32_16x16x32_bf16 v[40:43], v[152:155], v[184:187], v[40:43]
	v_mfma_f32_16x16x32_bf16 v[28:31], v[138:141], v[196:199], v[28:31]
	v_mfma_f32_16x16x32_bf16 v[24:27], v[152:155], v[196:199], v[24:27]
	v_mfma_f32_16x16x32_bf16 v[12:15], v[138:141], v[204:207], v[12:15]
	v_mfma_f32_16x16x32_bf16 v[8:11], v[152:155], v[204:207], v[8:11]
	v_mfma_f32_16x16x32_bf16 v[60:63], v[148:151], v[180:183], v[60:63]
	v_mfma_f32_16x16x32_bf16 v[56:59], v[156:159], v[180:183], v[56:59]
	v_mfma_f32_16x16x32_bf16 v[44:47], v[148:151], v[188:191], v[44:47]
	v_mfma_f32_16x16x32_bf16 v[40:43], v[156:159], v[188:191], v[40:43]
	v_mfma_f32_16x16x32_bf16 v[28:31], v[148:151], v[200:203], v[28:31]
	v_mfma_f32_16x16x32_bf16 v[24:27], v[156:159], v[200:203], v[24:27]
	v_mfma_f32_16x16x32_bf16 v[12:15], v[148:151], v[208:211], v[12:15]
	v_mfma_f32_16x16x32_bf16 v[8:11], v[156:159], v[208:211], v[8:11]
	v_mfma_f32_16x16x32_bf16 v[52:55], v[160:163], v[176:179], v[52:55]
	v_mfma_f32_16x16x32_bf16 v[48:51], v[168:171], v[176:179], v[48:51]
	v_mfma_f32_16x16x32_bf16 v[36:39], v[160:163], v[184:187], v[36:39]
	v_mfma_f32_16x16x32_bf16 v[32:35], v[168:171], v[184:187], v[32:35]
	v_mfma_f32_16x16x32_bf16 v[20:23], v[160:163], v[196:199], v[20:23]
	v_mfma_f32_16x16x32_bf16 v[16:19], v[168:171], v[196:199], v[16:19]
	v_mfma_f32_16x16x32_bf16 v[4:7], v[160:163], v[204:207], v[4:7]
	v_mfma_f32_16x16x32_bf16 v[0:3], v[168:171], v[204:207], v[0:3]
	v_mfma_f32_16x16x32_bf16 v[52:55], v[164:167], v[180:183], v[52:55]
	v_mfma_f32_16x16x32_bf16 v[48:51], v[172:175], v[180:183], v[48:51]
	v_mfma_f32_16x16x32_bf16 v[36:39], v[164:167], v[188:191], v[36:39]
	v_mfma_f32_16x16x32_bf16 v[32:35], v[172:175], v[188:191], v[32:35]
	v_mfma_f32_16x16x32_bf16 v[20:23], v[164:167], v[200:203], v[20:23]
	v_mfma_f32_16x16x32_bf16 v[16:19], v[172:175], v[200:203], v[16:19]
	v_mfma_f32_16x16x32_bf16 v[4:7], v[164:167], v[208:211], v[4:7]
	v_mfma_f32_16x16x32_bf16 v[0:3], v[172:175], v[208:211], v[0:3]
	s_setprio 0
	s_barrier
	s_add_i32 s12, 0, 0x18000
	v_add_u32_e32 v142, s12, v144
	s_add_i32 s13, 0, 0x1c000
	ds_read_b128 v[138:141], v142
	ds_read_b128 v[148:151], v142 offset:1024
	ds_read_b128 v[152:155], v142 offset:2048
	ds_read_b128 v[156:159], v142 offset:3072
	v_add_u32_e32 v142, s13, v144
	ds_read_b128 v[160:163], v142
	ds_read_b128 v[164:167], v142 offset:1024
	ds_read_b128 v[168:171], v142 offset:2048
	ds_read_b128 v[172:175], v142 offset:3072
	s_add_u32 s10, s84, 0x40000
	s_addc_u32 s11, s85, 0
	s_mov_b32 m0, s87
	v_lshl_add_u64 v[220:221], s[10:11], 0, v[128:129]
	ds_read_b128 v[176:179], v147 offset:32768
	ds_read_b128 v[180:183], v147 offset:33792
	ds_read_b128 v[184:187], v147 offset:34816
	ds_read_b128 v[188:191], v147 offset:35840
	ds_read_b128 v[196:199], v147 offset:36864
	ds_read_b128 v[200:203], v147 offset:37888
	ds_read_b128 v[204:207], v147 offset:38912
	ds_read_b128 v[208:211], v147 offset:39936
	global_load_lds_dwordx4 v[220:221], off
	v_lshl_add_u64 v[220:221], s[10:11], 0, v[130:131]
	s_mov_b32 m0, s88
	s_nop 0
	global_load_lds_dwordx4 v[220:221], off
	s_waitcnt vmcnt(8)
	s_waitcnt lgkmcnt(0)
	s_barrier
	s_setprio 1
	s_waitcnt lgkmcnt(0)
	v_mfma_f32_16x16x32_bf16 v[124:127], v[138:141], v[176:179], v[124:127]
	v_mfma_f32_16x16x32_bf16 v[120:123], v[152:155], v[176:179], v[120:123]
	v_mfma_f32_16x16x32_bf16 v[108:111], v[138:141], v[184:187], v[108:111]
	v_mfma_f32_16x16x32_bf16 v[104:107], v[152:155], v[184:187], v[104:107]
	v_mfma_f32_16x16x32_bf16 v[92:95], v[138:141], v[196:199], v[92:95]
	v_mfma_f32_16x16x32_bf16 v[88:91], v[152:155], v[196:199], v[88:91]
	v_mfma_f32_16x16x32_bf16 v[76:79], v[138:141], v[204:207], v[76:79]
	v_mfma_f32_16x16x32_bf16 v[72:75], v[152:155], v[204:207], v[72:75]
	v_mfma_f32_16x16x32_bf16 v[124:127], v[148:151], v[180:183], v[124:127]
	v_mfma_f32_16x16x32_bf16 v[120:123], v[156:159], v[180:183], v[120:123]
	v_mfma_f32_16x16x32_bf16 v[108:111], v[148:151], v[188:191], v[108:111]
	v_mfma_f32_16x16x32_bf16 v[104:107], v[156:159], v[188:191], v[104:107]
	v_mfma_f32_16x16x32_bf16 v[92:95], v[148:151], v[200:203], v[92:95]
	v_mfma_f32_16x16x32_bf16 v[88:91], v[156:159], v[200:203], v[88:91]
	v_mfma_f32_16x16x32_bf16 v[76:79], v[148:151], v[208:211], v[76:79]
	v_mfma_f32_16x16x32_bf16 v[72:75], v[156:159], v[208:211], v[72:75]
	v_mfma_f32_16x16x32_bf16 v[116:119], v[160:163], v[176:179], v[116:119]
	v_mfma_f32_16x16x32_bf16 v[112:115], v[168:171], v[176:179], v[112:115]
	v_mfma_f32_16x16x32_bf16 v[100:103], v[160:163], v[184:187], v[100:103]
	v_mfma_f32_16x16x32_bf16 v[96:99], v[168:171], v[184:187], v[96:99]
	v_mfma_f32_16x16x32_bf16 v[84:87], v[160:163], v[196:199], v[84:87]
	v_mfma_f32_16x16x32_bf16 v[80:83], v[168:171], v[196:199], v[80:83]
	v_mfma_f32_16x16x32_bf16 v[68:71], v[160:163], v[204:207], v[68:71]
	v_mfma_f32_16x16x32_bf16 v[64:67], v[168:171], v[204:207], v[64:67]
	v_mfma_f32_16x16x32_bf16 v[116:119], v[164:167], v[180:183], v[116:119]
	v_mfma_f32_16x16x32_bf16 v[112:115], v[172:175], v[180:183], v[112:115]
	v_mfma_f32_16x16x32_bf16 v[100:103], v[164:167], v[188:191], v[100:103]
	v_mfma_f32_16x16x32_bf16 v[96:99], v[172:175], v[188:191], v[96:99]
	v_mfma_f32_16x16x32_bf16 v[84:87], v[164:167], v[200:203], v[84:87]
	v_mfma_f32_16x16x32_bf16 v[80:83], v[172:175], v[200:203], v[80:83]
	v_mfma_f32_16x16x32_bf16 v[68:71], v[164:167], v[208:211], v[68:71]
	v_mfma_f32_16x16x32_bf16 v[64:67], v[172:175], v[208:211], v[64:67]
	s_setprio 0
	s_barrier
; #define PG8_STAGE(bufoff, gbase, voff) do { _Pragma("unroll") for (int _i = 0; _i < 2; ++_i) \
;         __builtin_amdgcn_global_load_lds((const unsigned*)((const char*)(gbase) + (voff)[_i]), (PG8_LAS unsigned*)(lds + (bufoff) + ldsw + _i * 8192), 16, 0, 0); } while (0)
; #define PG8_LDA(dst, b, h) do { _Pragma("unroll") for (int m = 0; m < 4; ++m) _Pragma("unroll") for (int k = 0; k < 2; ++k) dst[m][k] = *(const PG8_LAS bf16x8*)(lds + PG8_SA(b, h) + aoff + m * 2048 + k * 1024); } while (0)
; #define PG8_MMA(ai, bj, At, Bt) do { __builtin_amdgcn_s_setprio(1); _Pragma("unroll") for (int m = 0; m < 4; ++m) _Pragma("unroll") for (int n = 0; n < 2; ++n) _Pragma("unroll") for (int k = 0; k < 2; ++k) \
;         acc[ai][bj][m][n] = __builtin_amdgcn_mfma_f32_16x16x32_bf16(Bt[n][k], At[m][k], acc[ai][bj][m][n], 0, 0, 0); __builtin_amdgcn_s_setprio(0); } while (0)
; #define PG8_WAIT_V(n) asm volatile("s_waitcnt vmcnt(" #n ")" ::: "memory")
; #define PG8_WAIT_L(n) asm volatile("s_waitcnt lgkmcnt(" #n ")" ::: "memory")
; #define PG8_BAR __builtin_amdgcn_s_barrier()
; #define PG8_SCHED __builtin_amdgcn_sched_barrier(0)
; template <class Epi, class Sched, bool ALIGN_EPI = false, bool SP2 = false>
; __device__ __forceinline__ void gemm_phase(PG8_LAS unsigned char* lds, const Gemm g, const Sched& S, const Epi& E, const int tid) {
;     ...
;             PG8_LDA(At, 1, 1); PG8_STAGE(PG8_SB(1, 0), b3, voffB); PG8_STAGE(PG8_SB(1, 1), b3 + hstep, voffB); PG8_STAGE(PG8_SA(1, 0), a3, voffA);
;             PG8_WAIT_V(8); PG8_WAIT_L(0); PG8_BAR; PG8_MMA(1, 0, At, B0); PG8_MMA(1, 1, At, B1); PG8_BAR; PG8_SCHED;
;     ...
;         if constexpr (ALIGN_EPI) { if (wr == 0) PG8_BAR; }
	s_add_i32 s10, s12, s6
	v_lshl_add_u64 v[212:213], v[212:213], 0, s[22:23]
	s_mov_b32 m0, s10
	ds_read_b128 v[176:179], v147 offset:49152
	ds_read_b128 v[180:183], v147 offset:50176
	ds_read_b128 v[184:187], v147 offset:51200
	ds_read_b128 v[188:191], v147 offset:52224
	ds_read_b128 v[196:199], v147 offset:53248
	ds_read_b128 v[200:203], v147 offset:54272
	ds_read_b128 v[204:207], v147 offset:55296
	ds_read_b128 v[208:211], v147 offset:56320
	global_load_lds_dwordx4 v[212:213], off
	s_add_i32 m0, s10, 0x2000
	s_add_u32 s10, s66, 0x40080
	v_lshl_add_u64 v[212:213], v[214:215], 0, s[22:23]
	s_addc_u32 s11, s67, 0
	s_add_i32 s12, s13, s6
	global_load_lds_dwordx4 v[212:213], off
	v_lshl_add_u64 v[212:213], s[10:11], 0, v[192:193]
	s_mov_b32 m0, s12
	s_nop 0
	global_load_lds_dwordx4 v[212:213], off
	v_lshl_add_u64 v[212:213], s[10:11], 0, v[132:133]
	s_add_i32 m0, s12, 0x2000
	s_nop 0
	global_load_lds_dwordx4 v[212:213], off
	v_lshl_add_u64 v[212:213], v[216:217], 0, s[22:23]
	s_mov_b32 m0, s89
	s_nop 0
	global_load_lds_dwordx4 v[212:213], off
	v_lshl_add_u64 v[212:213], v[218:219], 0, s[22:23]
	s_mov_b32 m0, s92
	s_nop 0
	global_load_lds_dwordx4 v[212:213], off
	s_waitcnt vmcnt(8)
	s_waitcnt lgkmcnt(0)
	s_barrier
	s_setprio 1
	s_waitcnt lgkmcnt(0)
	v_mfma_f32_16x16x32_bf16 v[60:63], v[138:141], v[176:179], v[60:63]
	v_mfma_f32_16x16x32_bf16 v[56:59], v[152:155], v[176:179], v[56:59]
	v_mfma_f32_16x16x32_bf16 v[44:47], v[138:141], v[184:187], v[44:47]
	v_mfma_f32_16x16x32_bf16 v[40:43], v[152:155], v[184:187], v[40:43]
	v_mfma_f32_16x16x32_bf16 v[28:31], v[138:141], v[196:199], v[28:31]
	v_mfma_f32_16x16x32_bf16 v[24:27], v[152:155], v[196:199], v[24:27]
	v_mfma_f32_16x16x32_bf16 v[12:15], v[138:141], v[204:207], v[12:15]
	v_mfma_f32_16x16x32_bf16 v[8:11], v[152:155], v[204:207], v[8:11]
	v_mfma_f32_16x16x32_bf16 v[60:63], v[148:151], v[180:183], v[60:63]
	v_mfma_f32_16x16x32_bf16 v[56:59], v[156:159], v[180:183], v[56:59]
	v_mfma_f32_16x16x32_bf16 v[44:47], v[148:151], v[188:191], v[44:47]
	v_mfma_f32_16x16x32_bf16 v[40:43], v[156:159], v[188:191], v[40:43]
	v_mfma_f32_16x16x32_bf16 v[28:31], v[148:151], v[200:203], v[28:31]
	v_mfma_f32_16x16x32_bf16 v[24:27], v[156:159], v[200:203], v[24:27]
	v_mfma_f32_16x16x32_bf16 v[12:15], v[148:151], v[208:211], v[12:15]
	v_mfma_f32_16x16x32_bf16 v[8:11], v[156:159], v[208:211], v[8:11]
	v_mfma_f32_16x16x32_bf16 v[52:55], v[160:163], v[176:179], v[52:55]
	v_mfma_f32_16x16x32_bf16 v[48:51], v[168:171], v[176:179], v[48:51]
	v_mfma_f32_16x16x32_bf16 v[36:39], v[160:163], v[184:187], v[36:39]
	v_mfma_f32_16x16x32_bf16 v[32:35], v[168:171], v[184:187], v[32:35]
	v_mfma_f32_16x16x32_bf16 v[20:23], v[160:163], v[196:199], v[20:23]
	v_mfma_f32_16x16x32_bf16 v[16:19], v[168:171], v[196:199], v[16:19]
	v_mfma_f32_16x16x32_bf16 v[4:7], v[160:163], v[204:207], v[4:7]
	v_mfma_f32_16x16x32_bf16 v[0:3], v[168:171], v[204:207], v[0:3]
	v_mfma_f32_16x16x32_bf16 v[52:55], v[164:167], v[180:183], v[52:55]
	v_mfma_f32_16x16x32_bf16 v[48:51], v[172:175], v[180:183], v[48:51]
	v_mfma_f32_16x16x32_bf16 v[36:39], v[164:167], v[188:191], v[36:39]
	v_mfma_f32_16x16x32_bf16 v[32:35], v[172:175], v[188:191], v[32:35]
	v_mfma_f32_16x16x32_bf16 v[20:23], v[164:167], v[200:203], v[20:23]
	v_mfma_f32_16x16x32_bf16 v[16:19], v[172:175], v[200:203], v[16:19]
	v_mfma_f32_16x16x32_bf16 v[4:7], v[164:167], v[208:211], v[4:7]
	v_mfma_f32_16x16x32_bf16 v[0:3], v[172:175], v[208:211], v[0:3]
	s_setprio 0
	s_barrier
	s_add_i32 s9, s9, 2
	s_add_u32 s64, s64, 0x100
	s_addc_u32 s65, s65, 0
	s_add_u32 s96, s96, 0x100
	s_addc_u32 s8, s8, 0
	s_cmp_gt_u32 s9, 13
	s_cbranch_scc0 .LBB0_270
	s_and_b64 vcc, exec, s[54:55]
	s_cbranch_vccz .LBB0_273
	s_barrier

; #define PG8_STAGE(bufoff, gbase, voff) do { _Pragma("unroll") for (int _i = 0; _i < 2; ++_i) \
;         __builtin_amdgcn_global_load_lds((const unsigned*)((const char*)(gbase) + (voff)[_i]), (PG8_LAS unsigned*)(lds + (bufoff) + ldsw + _i * 8192), 16, 0, 0); } while (0)
; #define PG8_LDA(dst, b, h) do { _Pragma("unroll") for (int m = 0; m < 4; ++m) _Pragma("unroll") for (int k = 0; k < 2; ++k) dst[m][k] = *(const PG8_LAS bf16x8*)(lds + PG8_SA(b, h) + aoff + m * 2048 + k * 1024); } while (0)
; #define PG8_LDB(dst, b, h) do { _Pragma("unroll") for (int n = 0; n < 2; ++n) _Pragma("unroll") for (int k = 0; k < 2; ++k) dst[n][k] = *(const PG8_LAS bf16x8*)(lds + PG8_SB(b, h) + boff + n * 2048 + k * 1024); } while (0)
; #define PG8_MMA(ai, bj, At, Bt) do { __builtin_amdgcn_s_setprio(1); _Pragma("unroll") for (int m = 0; m < 4; ++m) _Pragma("unroll") for (int n = 0; n < 2; ++n) _Pragma("unroll") for (int k = 0; k < 2; ++k) \
;         acc[ai][bj][m][n] = __builtin_amdgcn_mfma_f32_16x16x32_bf16(Bt[n][k], At[m][k], acc[ai][bj][m][n], 0, 0, 0); __builtin_amdgcn_s_setprio(0); } while (0)
; #define PG8_WAIT_V(n) asm volatile("s_waitcnt vmcnt(" #n ")" ::: "memory")
; #define PG8_WAIT_L(n) asm volatile("s_waitcnt lgkmcnt(" #n ")" ::: "memory")
; #define PG8_BAR __builtin_amdgcn_s_barrier()
; #define PG8_SCHED __builtin_amdgcn_sched_barrier(0)
; template <class Epi, class Sched, bool ALIGN_EPI = false, bool SP2 = false>
; __device__ __forceinline__ void gemm_phase(PG8_LAS unsigned char* lds, const Gemm g, const Sched& S, const Epi& E, const int tid) {
;     ...
;             PG8_LDB(B0, 0, 0); PG8_LDB(B1, 0, 1); PG8_SCHED; PG8_LDA(At, 0, 0); PG8_STAGE(PG8_SA(1, 1), a1 + hstep, voffA);
;             PG8_WAIT_V(8); PG8_WAIT_L(0); PG8_BAR; PG8_MMA(0, 0, At, B0); PG8_MMA(0, 1, At, B1); PG8_BAR; PG8_SCHED;
;             PG8_LDA(At, 0, 1); PG8_STAGE(PG8_SB(0, 0), b2, voffB); PG8_STAGE(PG8_SB(0, 1), b2 + hstep, voffB); PG8_STAGE(PG8_SA(0, 0), a2, voffA);
;             PG8_WAIT_V(8); PG8_WAIT_L(0); PG8_BAR; PG8_MMA(1, 0, At, B0); PG8_MMA(1, 1, At, B1); PG8_BAR; PG8_SCHED;
.LBB0_326:
	s_add_u32 s10, vcc_lo, 0xfffc0080
	s_addc_u32 s11, vcc_hi, -1
	s_add_i32 s12, 0, 0x10000
	s_cmp_eq_u32 s9, 12
	s_cselect_b32 s85, s1, s11
	s_cselect_b32 s84, s31, s10
	s_cselect_b32 s67, s61, s8
	s_cselect_b32 s66, s65, s82
	s_add_i32 s13, 0, 0x14000
	v_add_u32_e32 v140, s12, v248
	v_add_u32_e32 v156, s13, v248
	ds_read_b128 v[128:131], v140
	ds_read_b128 v[132:135], v140 offset:1024
	ds_read_b128 v[136:139], v140 offset:2048
	ds_read_b128 v[140:143], v140 offset:3072
	ds_read_b128 v[144:147], v156
	ds_read_b128 v[148:151], v156 offset:1024
	ds_read_b128 v[152:155], v156 offset:2048
	ds_read_b128 v[156:159], v156 offset:3072
	v_lshl_add_u64 v[206:207], vcc, 0, v[202:203]
	s_add_i32 m0, s7, 0xc000
	ds_read_b128 v[160:163], v252
	ds_read_b128 v[164:167], v252 offset:1024
	ds_read_b128 v[168:171], v252 offset:2048
	ds_read_b128 v[172:175], v252 offset:3072
	ds_read_b128 v[176:179], v252 offset:4096
	ds_read_b128 v[180:183], v252 offset:5120
	ds_read_b128 v[184:187], v252 offset:6144
	ds_read_b128 v[188:191], v252 offset:7168
	global_load_lds_dwordx4 v[206:207], off
	v_lshl_add_u64 v[206:207], vcc, 0, v[204:205]
	s_add_i32 m0, s7, 0xe000
	s_nop 0
	global_load_lds_dwordx4 v[206:207], off
	s_waitcnt vmcnt(8)
	s_waitcnt lgkmcnt(0)
	s_barrier
	s_setprio 1
	s_waitcnt lgkmcnt(0)
	v_mfma_f32_16x16x32_bf16 v[124:127], v[128:131], v[160:163], v[124:127]
	v_mfma_f32_16x16x32_bf16 v[120:123], v[136:139], v[160:163], v[120:123]
	v_mfma_f32_16x16x32_bf16 v[108:111], v[128:131], v[168:171], v[108:111]
	v_mfma_f32_16x16x32_bf16 v[104:107], v[136:139], v[168:171], v[104:107]
	v_mfma_f32_16x16x32_bf16 v[92:95], v[128:131], v[176:179], v[92:95]
	v_mfma_f32_16x16x32_bf16 v[88:91], v[136:139], v[176:179], v[88:91]
	v_mfma_f32_16x16x32_bf16 v[76:79], v[128:131], v[184:187], v[76:79]
	v_mfma_f32_16x16x32_bf16 v[72:75], v[136:139], v[184:187], v[72:75]
	v_mfma_f32_16x16x32_bf16 v[124:127], v[132:135], v[164:167], v[124:127]
	v_mfma_f32_16x16x32_bf16 v[120:123], v[140:143], v[164:167], v[120:123]
	v_mfma_f32_16x16x32_bf16 v[108:111], v[132:135], v[172:175], v[108:111]
	v_mfma_f32_16x16x32_bf16 v[104:107], v[140:143], v[172:175], v[104:107]
	v_mfma_f32_16x16x32_bf16 v[92:95], v[132:135], v[180:183], v[92:95]
	v_mfma_f32_16x16x32_bf16 v[88:91], v[140:143], v[180:183], v[88:91]
	v_mfma_f32_16x16x32_bf16 v[76:79], v[132:135], v[188:191], v[76:79]
	v_mfma_f32_16x16x32_bf16 v[72:75], v[140:143], v[188:191], v[72:75]
	v_mfma_f32_16x16x32_bf16 v[116:119], v[144:147], v[160:163], v[116:119]
	v_mfma_f32_16x16x32_bf16 v[112:115], v[152:155], v[160:163], v[112:115]
	v_mfma_f32_16x16x32_bf16 v[100:103], v[144:147], v[168:171], v[100:103]
	v_mfma_f32_16x16x32_bf16 v[96:99], v[152:155], v[168:171], v[96:99]
	v_mfma_f32_16x16x32_bf16 v[84:87], v[144:147], v[176:179], v[84:87]
	v_mfma_f32_16x16x32_bf16 v[80:83], v[152:155], v[176:179], v[80:83]
	v_mfma_f32_16x16x32_bf16 v[68:71], v[144:147], v[184:187], v[68:71]
	v_mfma_f32_16x16x32_bf16 v[64:67], v[152:155], v[184:187], v[64:67]
	v_mfma_f32_16x16x32_bf16 v[116:119], v[148:151], v[164:167], v[116:119]
	v_mfma_f32_16x16x32_bf16 v[112:115], v[156:159], v[164:167], v[112:115]
	v_mfma_f32_16x16x32_bf16 v[100:103], v[148:151], v[172:175], v[100:103]
	v_mfma_f32_16x16x32_bf16 v[96:99], v[156:159], v[172:175], v[96:99]
	v_mfma_f32_16x16x32_bf16 v[84:87], v[148:151], v[180:183], v[84:87]
	v_mfma_f32_16x16x32_bf16 v[80:83], v[156:159], v[180:183], v[80:83]
	v_mfma_f32_16x16x32_bf16 v[68:71], v[148:151], v[188:191], v[68:71]
	v_mfma_f32_16x16x32_bf16 v[64:67], v[156:159], v[188:191], v[64:67]
	s_setprio 0
	s_barrier
	s_add_i32 s10, s12, s4
	v_lshl_add_u64 v[206:207], s[66:67], 0, v[192:193]
	s_mov_b32 m0, s10
	ds_read_b128 v[160:163], v252 offset:16384
	ds_read_b128 v[164:167], v252 offset:17408
	ds_read_b128 v[168:171], v252 offset:18432
	ds_read_b128 v[172:175], v252 offset:19456
	ds_read_b128 v[176:179], v252 offset:20480
	ds_read_b128 v[180:183], v252 offset:21504
	ds_read_b128 v[184:187], v252 offset:22528
	ds_read_b128 v[188:191], v252 offset:23552
	global_load_lds_dwordx4 v[206:207], off
	s_add_i32 m0, s10, 0x2000
	s_add_u32 s10, s66, 0x40000
	v_lshl_add_u64 v[208:209], s[66:67], 0, v[200:201]
	s_addc_u32 s11, s67, 0
	s_add_i32 s12, s13, s4
	global_load_lds_dwordx4 v[208:209], off
	v_lshl_add_u64 v[210:211], s[10:11], 0, v[192:193]
	s_mov_b32 m0, s12
	v_lshl_add_u64 v[212:213], s[84:85], 0, v[198:199]
	global_load_lds_dwordx4 v[210:211], off
	v_lshl_add_u64 v[210:211], s[10:11], 0, v[200:201]
	s_add_i32 m0, s12, 0x2000
	s_nop 0
	global_load_lds_dwordx4 v[210:211], off
	v_lshl_add_u64 v[210:211], s[84:85], 0, v[196:197]
	s_mov_b32 m0, s7
	s_nop 0
	global_load_lds_dwordx4 v[210:211], off
	s_mov_b32 m0, s76
	s_nop 0
	global_load_lds_dwordx4 v[212:213], off
	s_waitcnt vmcnt(8)
	s_waitcnt lgkmcnt(0)
	s_barrier
; #define PG8_STAGE(bufoff, gbase, voff) do { _Pragma("unroll") for (int _i = 0; _i < 2; ++_i) \
;         __builtin_amdgcn_global_load_lds((const unsigned*)((const char*)(gbase) + (voff)[_i]), (PG8_LAS unsigned*)(lds + (bufoff) + ldsw + _i * 8192), 16, 0, 0); } while (0)
; #define PG8_LDA(dst, b, h) do { _Pragma("unroll") for (int m = 0; m < 4; ++m) _Pragma("unroll") for (int k = 0; k < 2; ++k) dst[m][k] = *(const PG8_LAS bf16x8*)(lds + PG8_SA(b, h) + aoff + m * 2048 + k * 1024); } while (0)
; #define PG8_LDB(dst, b, h) do { _Pragma("unroll") for (int n = 0; n < 2; ++n) _Pragma("unroll") for (int k = 0; k < 2; ++k) dst[n][k] = *(const PG8_LAS bf16x8*)(lds + PG8_SB(b, h) + boff + n * 2048 + k * 1024); } while (0)
; #define PG8_MMA(ai, bj, At, Bt) do { __builtin_amdgcn_s_setprio(1); _Pragma("unroll") for (int m = 0; m < 4; ++m) _Pragma("unroll") for (int n = 0; n < 2; ++n) _Pragma("unroll") for (int k = 0; k < 2; ++k) \
;         acc[ai][bj][m][n] = __builtin_amdgcn_mfma_f32_16x16x32_bf16(Bt[n][k], At[m][k], acc[ai][bj][m][n], 0, 0, 0); __builtin_amdgcn_s_setprio(0); } while (0)
; #define PG8_WAIT_V(n) asm volatile("s_waitcnt vmcnt(" #n ")" ::: "memory")
; #define PG8_WAIT_L(n) asm volatile("s_waitcnt lgkmcnt(" #n ")" ::: "memory")
; #define PG8_BAR __builtin_amdgcn_s_barrier()
; #define PG8_SCHED __builtin_amdgcn_sched_barrier(0)
; template <class Epi, class Sched, bool ALIGN_EPI = false, bool SP2 = false>
; __device__ __forceinline__ void gemm_phase(PG8_LAS unsigned char* lds, const Gemm g, const Sched& S, const Epi& E, const int tid) {
;     ...
;             PG8_WAIT_V(8); PG8_WAIT_L(0); PG8_BAR; PG8_MMA(1, 0, At, B0); PG8_MMA(1, 1, At, B1); PG8_BAR; PG8_SCHED;
;             PG8_LDB(B0, 1, 0); PG8_LDB(B1, 1, 1); PG8_SCHED; PG8_LDA(At, 1, 0); PG8_STAGE(PG8_SA(0, 1), a2 + hstep, voffA);
;             PG8_WAIT_V(8); PG8_WAIT_L(0); PG8_BAR; PG8_MMA(0, 0, At, B0); PG8_MMA(0, 1, At, B1); PG8_BAR; PG8_SCHED;
	s_setprio 1
	s_waitcnt lgkmcnt(0)
	v_mfma_f32_16x16x32_bf16 v[60:63], v[128:131], v[160:163], v[60:63]
	v_mfma_f32_16x16x32_bf16 v[56:59], v[136:139], v[160:163], v[56:59]
	v_mfma_f32_16x16x32_bf16 v[44:47], v[128:131], v[168:171], v[44:47]
	v_mfma_f32_16x16x32_bf16 v[40:43], v[136:139], v[168:171], v[40:43]
	v_mfma_f32_16x16x32_bf16 v[28:31], v[128:131], v[176:179], v[28:31]
	v_mfma_f32_16x16x32_bf16 v[24:27], v[136:139], v[176:179], v[24:27]
	v_mfma_f32_16x16x32_bf16 v[12:15], v[128:131], v[184:187], v[12:15]
	v_mfma_f32_16x16x32_bf16 v[8:11], v[136:139], v[184:187], v[8:11]
	v_mfma_f32_16x16x32_bf16 v[60:63], v[132:135], v[164:167], v[60:63]
	v_mfma_f32_16x16x32_bf16 v[56:59], v[140:143], v[164:167], v[56:59]
	v_mfma_f32_16x16x32_bf16 v[44:47], v[132:135], v[172:175], v[44:47]
	v_mfma_f32_16x16x32_bf16 v[40:43], v[140:143], v[172:175], v[40:43]
	v_mfma_f32_16x16x32_bf16 v[28:31], v[132:135], v[180:183], v[28:31]
	v_mfma_f32_16x16x32_bf16 v[24:27], v[140:143], v[180:183], v[24:27]
	v_mfma_f32_16x16x32_bf16 v[12:15], v[132:135], v[188:191], v[12:15]
	v_mfma_f32_16x16x32_bf16 v[8:11], v[140:143], v[188:191], v[8:11]
	v_mfma_f32_16x16x32_bf16 v[52:55], v[144:147], v[160:163], v[52:55]
	v_mfma_f32_16x16x32_bf16 v[48:51], v[152:155], v[160:163], v[48:51]
	v_mfma_f32_16x16x32_bf16 v[36:39], v[144:147], v[168:171], v[36:39]
	v_mfma_f32_16x16x32_bf16 v[32:35], v[152:155], v[168:171], v[32:35]
	v_mfma_f32_16x16x32_bf16 v[20:23], v[144:147], v[176:179], v[20:23]
	v_mfma_f32_16x16x32_bf16 v[16:19], v[152:155], v[176:179], v[16:19]
	v_mfma_f32_16x16x32_bf16 v[4:7], v[144:147], v[184:187], v[4:7]
	v_mfma_f32_16x16x32_bf16 v[0:3], v[152:155], v[184:187], v[0:3]
	v_mfma_f32_16x16x32_bf16 v[52:55], v[148:151], v[164:167], v[52:55]
	v_mfma_f32_16x16x32_bf16 v[48:51], v[156:159], v[164:167], v[48:51]
	v_mfma_f32_16x16x32_bf16 v[36:39], v[148:151], v[172:175], v[36:39]
	v_mfma_f32_16x16x32_bf16 v[32:35], v[156:159], v[172:175], v[32:35]
	v_mfma_f32_16x16x32_bf16 v[20:23], v[148:151], v[180:183], v[20:23]
	v_mfma_f32_16x16x32_bf16 v[16:19], v[156:159], v[180:183], v[16:19]
	v_mfma_f32_16x16x32_bf16 v[4:7], v[148:151], v[188:191], v[4:7]
	v_mfma_f32_16x16x32_bf16 v[0:3], v[156:159], v[188:191], v[0:3]
	s_setprio 0
	s_barrier
	s_add_i32 s12, 0, 0x18000
	s_add_i32 s13, 0, 0x1c000
	v_add_u32_e32 v140, s12, v248
	v_add_u32_e32 v156, s13, v248
	ds_read_b128 v[128:131], v140
	ds_read_b128 v[132:135], v140 offset:1024
	ds_read_b128 v[136:139], v140 offset:2048
	ds_read_b128 v[140:143], v140 offset:3072
	ds_read_b128 v[144:147], v156
	ds_read_b128 v[148:151], v156 offset:1024
	ds_read_b128 v[152:155], v156 offset:2048
	ds_read_b128 v[156:159], v156 offset:3072
	s_add_u32 s10, s84, 0x40000
	s_addc_u32 s11, s85, 0
	s_mov_b32 m0, s77
	v_lshl_add_u64 v[214:215], s[10:11], 0, v[196:197]
	ds_read_b128 v[160:163], v252 offset:32768
	ds_read_b128 v[164:167], v252 offset:33792
	ds_read_b128 v[168:171], v252 offset:34816
	ds_read_b128 v[172:175], v252 offset:35840
	ds_read_b128 v[176:179], v252 offset:36864
	ds_read_b128 v[180:183], v252 offset:37888
	ds_read_b128 v[184:187], v252 offset:38912
	ds_read_b128 v[188:191], v252 offset:39936
	global_load_lds_dwordx4 v[214:215], off
	v_lshl_add_u64 v[214:215], s[10:11], 0, v[198:199]
	s_mov_b32 m0, s95
	s_nop 0
	global_load_lds_dwordx4 v[214:215], off
	s_waitcnt vmcnt(8)
	s_waitcnt lgkmcnt(0)
	s_barrier
	s_setprio 1
	s_waitcnt lgkmcnt(0)
	v_mfma_f32_16x16x32_bf16 v[124:127], v[128:131], v[160:163], v[124:127]
	v_mfma_f32_16x16x32_bf16 v[120:123], v[136:139], v[160:163], v[120:123]
	v_mfma_f32_16x16x32_bf16 v[108:111], v[128:131], v[168:171], v[108:111]
	v_mfma_f32_16x16x32_bf16 v[104:107], v[136:139], v[168:171], v[104:107]
	v_mfma_f32_16x16x32_bf16 v[92:95], v[128:131], v[176:179], v[92:95]
	v_mfma_f32_16x16x32_bf16 v[88:91], v[136:139], v[176:179], v[88:91]
	v_mfma_f32_16x16x32_bf16 v[76:79], v[128:131], v[184:187], v[76:79]
	v_mfma_f32_16x16x32_bf16 v[72:75], v[136:139], v[184:187], v[72:75]
	v_mfma_f32_16x16x32_bf16 v[124:127], v[132:135], v[164:167], v[124:127]
	v_mfma_f32_16x16x32_bf16 v[120:123], v[140:143], v[164:167], v[120:123]
	v_mfma_f32_16x16x32_bf16 v[108:111], v[132:135], v[172:175], v[108:111]
	v_mfma_f32_16x16x32_bf16 v[104:107], v[140:143], v[172:175], v[104:107]
	v_mfma_f32_16x16x32_bf16 v[92:95], v[132:135], v[180:183], v[92:95]
	v_mfma_f32_16x16x32_bf16 v[88:91], v[140:143], v[180:183], v[88:91]
	v_mfma_f32_16x16x32_bf16 v[76:79], v[132:135], v[188:191], v[76:79]
	v_mfma_f32_16x16x32_bf16 v[72:75], v[140:143], v[188:191], v[72:75]
	v_mfma_f32_16x16x32_bf16 v[116:119], v[144:147], v[160:163], v[116:119]
	v_mfma_f32_16x16x32_bf16 v[112:115], v[152:155], v[160:163], v[112:115]
	v_mfma_f32_16x16x32_bf16 v[100:103], v[144:147], v[168:171], v[100:103]
	v_mfma_f32_16x16x32_bf16 v[96:99], v[152:155], v[168:171], v[96:99]
	v_mfma_f32_16x16x32_bf16 v[84:87], v[144:147], v[176:179], v[84:87]
	v_mfma_f32_16x16x32_bf16 v[80:83], v[152:155], v[176:179], v[80:83]
	v_mfma_f32_16x16x32_bf16 v[68:71], v[144:147], v[184:187], v[68:71]
	v_mfma_f32_16x16x32_bf16 v[64:67], v[152:155], v[184:187], v[64:67]
	v_mfma_f32_16x16x32_bf16 v[116:119], v[148:151], v[164:167], v[116:119]
	v_mfma_f32_16x16x32_bf16 v[112:115], v[156:159], v[164:167], v[112:115]
	v_mfma_f32_16x16x32_bf16 v[100:103], v[148:151], v[172:175], v[100:103]
	v_mfma_f32_16x16x32_bf16 v[96:99], v[156:159], v[172:175], v[96:99]
	v_mfma_f32_16x16x32_bf16 v[84:87], v[148:151], v[180:183], v[84:87]
	v_mfma_f32_16x16x32_bf16 v[80:83], v[156:159], v[180:183], v[80:83]
	v_mfma_f32_16x16x32_bf16 v[68:71], v[148:151], v[188:191], v[68:71]
	v_mfma_f32_16x16x32_bf16 v[64:67], v[156:159], v[188:191], v[64:67]
	s_setprio 0
	s_barrier
; #define PG8_STAGE(bufoff, gbase, voff) do { _Pragma("unroll") for (int _i = 0; _i < 2; ++_i) \
;         __builtin_amdgcn_global_load_lds((const unsigned*)((const char*)(gbase) + (voff)[_i]), (PG8_LAS unsigned*)(lds + (bufoff) + ldsw + _i * 8192), 16, 0, 0); } while (0)
; #define PG8_LDA(dst, b, h) do { _Pragma("unroll") for (int m = 0; m < 4; ++m) _Pragma("unroll") for (int k = 0; k < 2; ++k) dst[m][k] = *(const PG8_LAS bf16x8*)(lds + PG8_SA(b, h) + aoff + m * 2048 + k * 1024); } while (0)
; #define PG8_MMA(ai, bj, At, Bt) do { __builtin_amdgcn_s_setprio(1); _Pragma("unroll") for (int m = 0; m < 4; ++m) _Pragma("unroll") for (int n = 0; n < 2; ++n) _Pragma("unroll") for (int k = 0; k < 2; ++k) \
;         acc[ai][bj][m][n] = __builtin_amdgcn_mfma_f32_16x16x32_bf16(Bt[n][k], At[m][k], acc[ai][bj][m][n], 0, 0, 0); __builtin_amdgcn_s_setprio(0); } while (0)
; #define PG8_WAIT_V(n) asm volatile("s_waitcnt vmcnt(" #n ")" ::: "memory")
; #define PG8_WAIT_L(n) asm volatile("s_waitcnt lgkmcnt(" #n ")" ::: "memory")
; #define PG8_BAR __builtin_amdgcn_s_barrier()
; #define PG8_SCHED __builtin_amdgcn_sched_barrier(0)
; template <class Epi, class Sched, bool ALIGN_EPI = false, bool SP2 = false>
; __device__ __forceinline__ void gemm_phase(PG8_LAS unsigned char* lds, const Gemm g, const Sched& S, const Epi& E, const int tid) {
;     ...
;             PG8_LDA(At, 1, 1); PG8_STAGE(PG8_SB(1, 0), b3, voffB); PG8_STAGE(PG8_SB(1, 1), b3 + hstep, voffB); PG8_STAGE(PG8_SA(1, 0), a3, voffA);
;             PG8_WAIT_V(8); PG8_WAIT_L(0); PG8_BAR; PG8_MMA(1, 0, At, B0); PG8_MMA(1, 1, At, B1); PG8_BAR; PG8_SCHED;
;     ...
;         if constexpr (ALIGN_EPI) { if (wr == 0) PG8_BAR; }
	s_add_i32 s10, s12, s4
	v_lshl_add_u64 v[206:207], v[206:207], 0, s[22:23]
	s_mov_b32 m0, s10
	ds_read_b128 v[160:163], v252 offset:49152
	ds_read_b128 v[164:167], v252 offset:50176
	ds_read_b128 v[168:171], v252 offset:51200
	ds_read_b128 v[172:175], v252 offset:52224
	ds_read_b128 v[176:179], v252 offset:53248
	ds_read_b128 v[180:183], v252 offset:54272
	ds_read_b128 v[184:187], v252 offset:55296
	ds_read_b128 v[188:191], v252 offset:56320
	global_load_lds_dwordx4 v[206:207], off
	s_add_i32 m0, s10, 0x2000
	s_add_u32 s10, s66, 0x40080
	v_lshl_add_u64 v[206:207], v[208:209], 0, s[22:23]
	s_addc_u32 s11, s67, 0
	s_add_i32 s12, s13, s4
	global_load_lds_dwordx4 v[206:207], off
	v_lshl_add_u64 v[206:207], s[10:11], 0, v[192:193]
	s_mov_b32 m0, s12
	s_nop 0
	global_load_lds_dwordx4 v[206:207], off
	v_lshl_add_u64 v[206:207], s[10:11], 0, v[200:201]
	s_add_i32 m0, s12, 0x2000
	s_nop 0
	global_load_lds_dwordx4 v[206:207], off
	v_lshl_add_u64 v[206:207], v[210:211], 0, s[22:23]
	s_mov_b32 m0, s92
	s_nop 0
	global_load_lds_dwordx4 v[206:207], off
	v_lshl_add_u64 v[206:207], v[212:213], 0, s[22:23]
	s_mov_b32 m0, s93
	s_nop 0
	global_load_lds_dwordx4 v[206:207], off
	s_waitcnt vmcnt(8)
	s_waitcnt lgkmcnt(0)
	s_barrier
	s_setprio 1
	s_waitcnt lgkmcnt(0)
	v_mfma_f32_16x16x32_bf16 v[60:63], v[128:131], v[160:163], v[60:63]
	v_mfma_f32_16x16x32_bf16 v[56:59], v[136:139], v[160:163], v[56:59]
	v_mfma_f32_16x16x32_bf16 v[44:47], v[128:131], v[168:171], v[44:47]
	v_mfma_f32_16x16x32_bf16 v[40:43], v[136:139], v[168:171], v[40:43]
	v_mfma_f32_16x16x32_bf16 v[28:31], v[128:131], v[176:179], v[28:31]
	v_mfma_f32_16x16x32_bf16 v[24:27], v[136:139], v[176:179], v[24:27]
	v_mfma_f32_16x16x32_bf16 v[12:15], v[128:131], v[184:187], v[12:15]
	v_mfma_f32_16x16x32_bf16 v[8:11], v[136:139], v[184:187], v[8:11]
	v_mfma_f32_16x16x32_bf16 v[60:63], v[132:135], v[164:167], v[60:63]
	v_mfma_f32_16x16x32_bf16 v[56:59], v[140:143], v[164:167], v[56:59]
	v_mfma_f32_16x16x32_bf16 v[44:47], v[132:135], v[172:175], v[44:47]
	v_mfma_f32_16x16x32_bf16 v[40:43], v[140:143], v[172:175], v[40:43]
	v_mfma_f32_16x16x32_bf16 v[28:31], v[132:135], v[180:183], v[28:31]
	v_mfma_f32_16x16x32_bf16 v[24:27], v[140:143], v[180:183], v[24:27]
	v_mfma_f32_16x16x32_bf16 v[12:15], v[132:135], v[188:191], v[12:15]
	v_mfma_f32_16x16x32_bf16 v[8:11], v[140:143], v[188:191], v[8:11]
	v_mfma_f32_16x16x32_bf16 v[52:55], v[144:147], v[160:163], v[52:55]
	v_mfma_f32_16x16x32_bf16 v[48:51], v[152:155], v[160:163], v[48:51]
	v_mfma_f32_16x16x32_bf16 v[36:39], v[144:147], v[168:171], v[36:39]
	v_mfma_f32_16x16x32_bf16 v[32:35], v[152:155], v[168:171], v[32:35]
	v_mfma_f32_16x16x32_bf16 v[20:23], v[144:147], v[176:179], v[20:23]
	v_mfma_f32_16x16x32_bf16 v[16:19], v[152:155], v[176:179], v[16:19]
	v_mfma_f32_16x16x32_bf16 v[4:7], v[144:147], v[184:187], v[4:7]
	v_mfma_f32_16x16x32_bf16 v[0:3], v[152:155], v[184:187], v[0:3]
	v_mfma_f32_16x16x32_bf16 v[52:55], v[148:151], v[164:167], v[52:55]
	v_mfma_f32_16x16x32_bf16 v[48:51], v[156:159], v[164:167], v[48:51]
	v_mfma_f32_16x16x32_bf16 v[36:39], v[148:151], v[172:175], v[36:39]
	v_mfma_f32_16x16x32_bf16 v[32:35], v[156:159], v[172:175], v[32:35]
	v_mfma_f32_16x16x32_bf16 v[20:23], v[148:151], v[180:183], v[20:23]
	v_mfma_f32_16x16x32_bf16 v[16:19], v[156:159], v[180:183], v[16:19]
	v_mfma_f32_16x16x32_bf16 v[4:7], v[148:151], v[188:191], v[4:7]
	v_mfma_f32_16x16x32_bf16 v[0:3], v[156:159], v[188:191], v[0:3]
	s_setprio 0
	s_barrier
	s_add_i32 s9, s9, 2
	s_add_u32 vcc_lo, vcc_lo, 0x100
	s_addc_u32 vcc_hi, vcc_hi, 0
	s_add_u32 s82, s82, 0x100
	s_addc_u32 s8, s8, 0
	s_cmp_gt_u32 s9, 13
	s_cbranch_scc0 .LBB0_326
	s_and_b64 vcc, exec, s[58:59]
	s_cbranch_vccz .LBB0_329
	s_barrier

; #define PG8_STAGE(bufoff, gbase, voff) do { _Pragma("unroll") for (int _i = 0; _i < 2; ++_i) \
;         __builtin_amdgcn_global_load_lds((const unsigned*)((const char*)(gbase) + (voff)[_i]), (PG8_LAS unsigned*)(lds + (bufoff) + ldsw + _i * 8192), 16, 0, 0); } while (0)
; #define PG8_LDA(dst, b, h) do { _Pragma("unroll") for (int m = 0; m < 4; ++m) _Pragma("unroll") for (int k = 0; k < 2; ++k) dst[m][k] = *(const PG8_LAS bf16x8*)(lds + PG8_SA(b, h) + aoff + m * 2048 + k * 1024); } while (0)
; #define PG8_LDB(dst, b, h) do { _Pragma("unroll") for (int n = 0; n < 2; ++n) _Pragma("unroll") for (int k = 0; k < 2; ++k) dst[n][k] = *(const PG8_LAS bf16x8*)(lds + PG8_SB(b, h) + boff + n * 2048 + k * 1024); } while (0)
; #define PG8_MMA(ai, bj, At, Bt) do { __builtin_amdgcn_s_setprio(1); _Pragma("unroll") for (int m = 0; m < 4; ++m) _Pragma("unroll") for (int n = 0; n < 2; ++n) _Pragma("unroll") for (int k = 0; k < 2; ++k) \
;         acc[ai][bj][m][n] = __builtin_amdgcn_mfma_f32_16x16x32_bf16(Bt[n][k], At[m][k], acc[ai][bj][m][n], 0, 0, 0); __builtin_amdgcn_s_setprio(0); } while (0)
; #define PG8_WAIT_V(n) asm volatile("s_waitcnt vmcnt(" #n ")" ::: "memory")
; #define PG8_WAIT_L(n) asm volatile("s_waitcnt lgkmcnt(" #n ")" ::: "memory")
; #define PG8_BAR __builtin_amdgcn_s_barrier()
; #define PG8_SCHED __builtin_amdgcn_sched_barrier(0)
; template <class Epi, class Sched, bool ALIGN_EPI = false, bool SP2 = false>
; __device__ __forceinline__ void gemm_phase(PG8_LAS unsigned char* lds, const Gemm g, const Sched& S, const Epi& E, const int tid) {
;     ...
;             PG8_LDB(B0, 0, 0); PG8_LDB(B1, 0, 1); PG8_SCHED; PG8_LDA(At, 0, 0); PG8_STAGE(PG8_SA(1, 1), a1 + hstep, voffA);
;             PG8_WAIT_V(8); PG8_WAIT_L(0); PG8_BAR; PG8_MMA(0, 0, At, B0); PG8_MMA(0, 1, At, B1); PG8_BAR; PG8_SCHED;
;             PG8_LDA(At, 0, 1); PG8_STAGE(PG8_SB(0, 0), b2, voffB); PG8_STAGE(PG8_SB(0, 1), b2 + hstep, voffB); PG8_STAGE(PG8_SA(0, 0), a2, voffA);
;             PG8_WAIT_V(8); PG8_WAIT_L(0); PG8_BAR; PG8_MMA(1, 0, At, B0); PG8_MMA(1, 1, At, B1); PG8_BAR; PG8_SCHED;
.LBB0_459:
	s_add_u32 s9, s0, 0xfffc0080
	s_addc_u32 s10, s1, -1
	s_add_i32 s11, 0, 0x10000
	s_cmp_eq_u32 s8, 12
	s_cselect_b32 s87, s45, s10
	s_cselect_b32 s86, s50, s9
	s_cselect_b32 s43, s51, s57
	s_cselect_b32 s42, s53, s56
	s_add_i32 s9, 0, 0x14000
	s_waitcnt vmcnt(0)
	v_add_u32_e32 v154, s11, v165
	v_add_u32_e32 v162, s9, v165
	ds_read_b128 v[142:145], v154
	ds_read_b128 v[146:149], v154 offset:1024
	ds_read_b128 v[150:153], v154 offset:2048
	ds_read_b128 v[154:157], v154 offset:3072
	ds_read_b128 v[158:161], v162
	ds_read_b128 v[188:191], v162 offset:1024
	ds_read_b128 v[196:199], v162 offset:2048
	ds_read_b128 v[200:203], v162 offset:3072
	v_lshl_add_u64 v[162:163], s[0:1], 0, v[138:139]
	s_add_i32 m0, s96, 0xc000
	ds_read_b128 v[204:207], v170
	ds_read_b128 v[208:211], v170 offset:1024
	ds_read_b128 v[212:215], v170 offset:2048
	ds_read_b128 v[216:219], v170 offset:3072
	ds_read_b128 v[220:223], v170 offset:4096
	ds_read_b128 v[224:227], v170 offset:5120
	ds_read_b128 v[228:231], v170 offset:6144
	ds_read_b128 v[232:235], v170 offset:7168
	global_load_lds_dwordx4 v[162:163], off
	v_lshl_add_u64 v[162:163], s[0:1], 0, v[140:141]
	s_add_i32 m0, s96, 0xe000
	s_nop 0
	global_load_lds_dwordx4 v[162:163], off
	s_waitcnt vmcnt(8)
	s_waitcnt lgkmcnt(0)
	s_barrier
	s_setprio 1
	s_waitcnt lgkmcnt(0)
	v_mfma_f32_16x16x32_bf16 v[124:127], v[142:145], v[204:207], v[124:127]
	v_mfma_f32_16x16x32_bf16 v[120:123], v[150:153], v[204:207], v[120:123]
	v_mfma_f32_16x16x32_bf16 v[108:111], v[142:145], v[212:215], v[108:111]
	v_mfma_f32_16x16x32_bf16 v[104:107], v[150:153], v[212:215], v[104:107]
	v_mfma_f32_16x16x32_bf16 v[92:95], v[142:145], v[220:223], v[92:95]
	v_mfma_f32_16x16x32_bf16 v[88:91], v[150:153], v[220:223], v[88:91]
	v_mfma_f32_16x16x32_bf16 v[76:79], v[142:145], v[228:231], v[76:79]
	v_mfma_f32_16x16x32_bf16 v[72:75], v[150:153], v[228:231], v[72:75]
	v_mfma_f32_16x16x32_bf16 v[124:127], v[146:149], v[208:211], v[124:127]
	v_mfma_f32_16x16x32_bf16 v[120:123], v[154:157], v[208:211], v[120:123]
	v_mfma_f32_16x16x32_bf16 v[108:111], v[146:149], v[216:219], v[108:111]
	v_mfma_f32_16x16x32_bf16 v[104:107], v[154:157], v[216:219], v[104:107]
	v_mfma_f32_16x16x32_bf16 v[92:95], v[146:149], v[224:227], v[92:95]
	v_mfma_f32_16x16x32_bf16 v[88:91], v[154:157], v[224:227], v[88:91]
	v_mfma_f32_16x16x32_bf16 v[76:79], v[146:149], v[232:235], v[76:79]
	v_mfma_f32_16x16x32_bf16 v[72:75], v[154:157], v[232:235], v[72:75]
	v_mfma_f32_16x16x32_bf16 v[116:119], v[158:161], v[204:207], v[116:119]
	v_mfma_f32_16x16x32_bf16 v[112:115], v[196:199], v[204:207], v[112:115]
	v_mfma_f32_16x16x32_bf16 v[100:103], v[158:161], v[212:215], v[100:103]
	v_mfma_f32_16x16x32_bf16 v[96:99], v[196:199], v[212:215], v[96:99]
	v_mfma_f32_16x16x32_bf16 v[84:87], v[158:161], v[220:223], v[84:87]
	v_mfma_f32_16x16x32_bf16 v[80:83], v[196:199], v[220:223], v[80:83]
	v_mfma_f32_16x16x32_bf16 v[68:71], v[158:161], v[228:231], v[68:71]
	v_mfma_f32_16x16x32_bf16 v[64:67], v[196:199], v[228:231], v[64:67]
	v_mfma_f32_16x16x32_bf16 v[116:119], v[188:191], v[208:211], v[116:119]
	v_mfma_f32_16x16x32_bf16 v[112:115], v[200:203], v[208:211], v[112:115]
	v_mfma_f32_16x16x32_bf16 v[100:103], v[188:191], v[216:219], v[100:103]
	v_mfma_f32_16x16x32_bf16 v[96:99], v[200:203], v[216:219], v[96:99]
	v_mfma_f32_16x16x32_bf16 v[84:87], v[188:191], v[224:227], v[84:87]
	v_mfma_f32_16x16x32_bf16 v[80:83], v[200:203], v[224:227], v[80:83]
	v_mfma_f32_16x16x32_bf16 v[68:71], v[188:191], v[232:235], v[68:71]
	v_mfma_f32_16x16x32_bf16 v[64:67], v[200:203], v[232:235], v[64:67]
	s_setprio 0
	s_barrier
	s_add_i32 s10, s11, s95
	v_lshl_add_u64 v[162:163], s[42:43], 0, v[130:131]
	s_mov_b32 m0, s10
	ds_read_b128 v[204:207], v170 offset:16384
	ds_read_b128 v[208:211], v170 offset:17408
	ds_read_b128 v[212:215], v170 offset:18432
	ds_read_b128 v[216:219], v170 offset:19456
	ds_read_b128 v[220:223], v170 offset:20480
	ds_read_b128 v[224:227], v170 offset:21504
	ds_read_b128 v[228:231], v170 offset:22528
	ds_read_b128 v[232:235], v170 offset:23552
	global_load_lds_dwordx4 v[162:163], off
	s_add_i32 m0, s10, 0x2000
	s_add_u32 s88, s42, 0x40000
	v_lshl_add_u64 v[236:237], s[42:43], 0, v[134:135]
	s_addc_u32 s89, s43, 0
	s_add_i32 s9, s9, s95
	global_load_lds_dwordx4 v[236:237], off
	v_lshl_add_u64 v[238:239], s[88:89], 0, v[130:131]
	s_mov_b32 m0, s9
	v_lshl_add_u64 v[240:241], s[86:87], 0, v[132:133]
	global_load_lds_dwordx4 v[238:239], off
	v_lshl_add_u64 v[238:239], s[88:89], 0, v[134:135]
	s_add_i32 m0, s9, 0x2000
	s_nop 0
	global_load_lds_dwordx4 v[238:239], off
	v_lshl_add_u64 v[238:239], s[86:87], 0, v[128:129]
	s_mov_b32 m0, s96
	s_nop 0
	global_load_lds_dwordx4 v[238:239], off
	s_mov_b32 m0, s97
	s_nop 0
	global_load_lds_dwordx4 v[240:241], off
	s_waitcnt vmcnt(8)
	s_waitcnt lgkmcnt(0)
	s_barrier
; #define PG8_STAGE(bufoff, gbase, voff) do { _Pragma("unroll") for (int _i = 0; _i < 2; ++_i) \
;         __builtin_amdgcn_global_load_lds((const unsigned*)((const char*)(gbase) + (voff)[_i]), (PG8_LAS unsigned*)(lds + (bufoff) + ldsw + _i * 8192), 16, 0, 0); } while (0)
; #define PG8_LDA(dst, b, h) do { _Pragma("unroll") for (int m = 0; m < 4; ++m) _Pragma("unroll") for (int k = 0; k < 2; ++k) dst[m][k] = *(const PG8_LAS bf16x8*)(lds + PG8_SA(b, h) + aoff + m * 2048 + k * 1024); } while (0)
; #define PG8_LDB(dst, b, h) do { _Pragma("unroll") for (int n = 0; n < 2; ++n) _Pragma("unroll") for (int k = 0; k < 2; ++k) dst[n][k] = *(const PG8_LAS bf16x8*)(lds + PG8_SB(b, h) + boff + n * 2048 + k * 1024); } while (0)
; #define PG8_MMA(ai, bj, At, Bt) do { __builtin_amdgcn_s_setprio(1); _Pragma("unroll") for (int m = 0; m < 4; ++m) _Pragma("unroll") for (int n = 0; n < 2; ++n) _Pragma("unroll") for (int k = 0; k < 2; ++k) \
;         acc[ai][bj][m][n] = __builtin_amdgcn_mfma_f32_16x16x32_bf16(Bt[n][k], At[m][k], acc[ai][bj][m][n], 0, 0, 0); __builtin_amdgcn_s_setprio(0); } while (0)
; #define PG8_WAIT_V(n) asm volatile("s_waitcnt vmcnt(" #n ")" ::: "memory")
; #define PG8_WAIT_L(n) asm volatile("s_waitcnt lgkmcnt(" #n ")" ::: "memory")
; #define PG8_BAR __builtin_amdgcn_s_barrier()
; #define PG8_SCHED __builtin_amdgcn_sched_barrier(0)
; template <class Epi, class Sched, bool ALIGN_EPI = false, bool SP2 = false>
; __device__ __forceinline__ void gemm_phase(PG8_LAS unsigned char* lds, const Gemm g, const Sched& S, const Epi& E, const int tid) {
;     ...
;             PG8_WAIT_V(8); PG8_WAIT_L(0); PG8_BAR; PG8_MMA(1, 0, At, B0); PG8_MMA(1, 1, At, B1); PG8_BAR; PG8_SCHED;
;             PG8_LDB(B0, 1, 0); PG8_LDB(B1, 1, 1); PG8_SCHED; PG8_LDA(At, 1, 0); PG8_STAGE(PG8_SA(0, 1), a2 + hstep, voffA);
;             PG8_WAIT_V(8); PG8_WAIT_L(0); PG8_BAR; PG8_MMA(0, 0, At, B0); PG8_MMA(0, 1, At, B1); PG8_BAR; PG8_SCHED;
	s_setprio 1
	s_waitcnt lgkmcnt(0)
	v_mfma_f32_16x16x32_bf16 v[60:63], v[142:145], v[204:207], v[60:63]
	v_mfma_f32_16x16x32_bf16 v[56:59], v[150:153], v[204:207], v[56:59]
	v_mfma_f32_16x16x32_bf16 v[44:47], v[142:145], v[212:215], v[44:47]
	v_mfma_f32_16x16x32_bf16 v[40:43], v[150:153], v[212:215], v[40:43]
	v_mfma_f32_16x16x32_bf16 v[28:31], v[142:145], v[220:223], v[28:31]
	v_mfma_f32_16x16x32_bf16 v[24:27], v[150:153], v[220:223], v[24:27]
	v_mfma_f32_16x16x32_bf16 v[12:15], v[142:145], v[228:231], v[12:15]
	v_mfma_f32_16x16x32_bf16 v[8:11], v[150:153], v[228:231], v[8:11]
	v_mfma_f32_16x16x32_bf16 v[60:63], v[146:149], v[208:211], v[60:63]
	v_mfma_f32_16x16x32_bf16 v[56:59], v[154:157], v[208:211], v[56:59]
	v_mfma_f32_16x16x32_bf16 v[44:47], v[146:149], v[216:219], v[44:47]
	v_mfma_f32_16x16x32_bf16 v[40:43], v[154:157], v[216:219], v[40:43]
	v_mfma_f32_16x16x32_bf16 v[28:31], v[146:149], v[224:227], v[28:31]
	v_mfma_f32_16x16x32_bf16 v[24:27], v[154:157], v[224:227], v[24:27]
	v_mfma_f32_16x16x32_bf16 v[12:15], v[146:149], v[232:235], v[12:15]
	v_mfma_f32_16x16x32_bf16 v[8:11], v[154:157], v[232:235], v[8:11]
	v_mfma_f32_16x16x32_bf16 v[52:55], v[158:161], v[204:207], v[52:55]
	v_mfma_f32_16x16x32_bf16 v[48:51], v[196:199], v[204:207], v[48:51]
	v_mfma_f32_16x16x32_bf16 v[36:39], v[158:161], v[212:215], v[36:39]
	v_mfma_f32_16x16x32_bf16 v[32:35], v[196:199], v[212:215], v[32:35]
	v_mfma_f32_16x16x32_bf16 v[20:23], v[158:161], v[220:223], v[20:23]
	v_mfma_f32_16x16x32_bf16 v[16:19], v[196:199], v[220:223], v[16:19]
	v_mfma_f32_16x16x32_bf16 v[4:7], v[158:161], v[228:231], v[4:7]
	v_mfma_f32_16x16x32_bf16 v[0:3], v[196:199], v[228:231], v[0:3]
	v_mfma_f32_16x16x32_bf16 v[52:55], v[188:191], v[208:211], v[52:55]
	v_mfma_f32_16x16x32_bf16 v[48:51], v[200:203], v[208:211], v[48:51]
	v_mfma_f32_16x16x32_bf16 v[36:39], v[188:191], v[216:219], v[36:39]
	v_mfma_f32_16x16x32_bf16 v[32:35], v[200:203], v[216:219], v[32:35]
	v_mfma_f32_16x16x32_bf16 v[20:23], v[188:191], v[224:227], v[20:23]
	v_mfma_f32_16x16x32_bf16 v[16:19], v[200:203], v[224:227], v[16:19]
	v_mfma_f32_16x16x32_bf16 v[4:7], v[188:191], v[232:235], v[4:7]
	v_mfma_f32_16x16x32_bf16 v[0:3], v[200:203], v[232:235], v[0:3]
	s_setprio 0
	s_barrier
	s_add_i32 s9, 0, 0x18000
	s_add_i32 s10, 0, 0x1c000
	v_add_u32_e32 v154, s9, v165
	v_add_u32_e32 v187, s10, v165
	ds_read_b128 v[142:145], v154
	ds_read_b128 v[146:149], v154 offset:1024
	ds_read_b128 v[150:153], v154 offset:2048
	ds_read_b128 v[154:157], v154 offset:3072
	ds_read_b128 v[158:161], v187
	ds_read_b128 v[188:191], v187 offset:1024
	ds_read_b128 v[196:199], v187 offset:2048
	ds_read_b128 v[200:203], v187 offset:3072
	s_add_u32 s86, s86, 0x40000
	s_addc_u32 s87, s87, 0
	s_mov_b32 m0, s76
	v_lshl_add_u64 v[248:249], s[86:87], 0, v[128:129]
	ds_read_b128 v[204:207], v170 offset:32768
	ds_read_b128 v[208:211], v170 offset:33792
	ds_read_b128 v[212:215], v170 offset:34816
	ds_read_b128 v[216:219], v170 offset:35840
	ds_read_b128 v[220:223], v170 offset:36864
	ds_read_b128 v[224:227], v170 offset:37888
	ds_read_b128 v[228:231], v170 offset:38912
	ds_read_b128 v[232:235], v170 offset:39936
	global_load_lds_dwordx4 v[248:249], off
	v_lshl_add_u64 v[248:249], s[86:87], 0, v[132:133]
	s_mov_b32 m0, s77
	s_nop 0
	global_load_lds_dwordx4 v[248:249], off
	s_waitcnt vmcnt(8)
	s_waitcnt lgkmcnt(0)
	s_barrier
	s_setprio 1
	s_waitcnt lgkmcnt(0)
	v_mfma_f32_16x16x32_bf16 v[124:127], v[142:145], v[204:207], v[124:127]
	v_mfma_f32_16x16x32_bf16 v[120:123], v[150:153], v[204:207], v[120:123]
	v_mfma_f32_16x16x32_bf16 v[108:111], v[142:145], v[212:215], v[108:111]
	v_mfma_f32_16x16x32_bf16 v[104:107], v[150:153], v[212:215], v[104:107]
	v_mfma_f32_16x16x32_bf16 v[92:95], v[142:145], v[220:223], v[92:95]
	v_mfma_f32_16x16x32_bf16 v[88:91], v[150:153], v[220:223], v[88:91]
	v_mfma_f32_16x16x32_bf16 v[76:79], v[142:145], v[228:231], v[76:79]
	v_mfma_f32_16x16x32_bf16 v[72:75], v[150:153], v[228:231], v[72:75]
	v_mfma_f32_16x16x32_bf16 v[124:127], v[146:149], v[208:211], v[124:127]
	v_mfma_f32_16x16x32_bf16 v[120:123], v[154:157], v[208:211], v[120:123]
	v_mfma_f32_16x16x32_bf16 v[108:111], v[146:149], v[216:219], v[108:111]
	v_mfma_f32_16x16x32_bf16 v[104:107], v[154:157], v[216:219], v[104:107]
	v_mfma_f32_16x16x32_bf16 v[92:95], v[146:149], v[224:227], v[92:95]
	v_mfma_f32_16x16x32_bf16 v[88:91], v[154:157], v[224:227], v[88:91]
	v_mfma_f32_16x16x32_bf16 v[76:79], v[146:149], v[232:235], v[76:79]
	v_mfma_f32_16x16x32_bf16 v[72:75], v[154:157], v[232:235], v[72:75]
	v_mfma_f32_16x16x32_bf16 v[116:119], v[158:161], v[204:207], v[116:119]
	v_mfma_f32_16x16x32_bf16 v[112:115], v[196:199], v[204:207], v[112:115]
	v_mfma_f32_16x16x32_bf16 v[100:103], v[158:161], v[212:215], v[100:103]
	v_mfma_f32_16x16x32_bf16 v[96:99], v[196:199], v[212:215], v[96:99]
	v_mfma_f32_16x16x32_bf16 v[84:87], v[158:161], v[220:223], v[84:87]
	v_mfma_f32_16x16x32_bf16 v[80:83], v[196:199], v[220:223], v[80:83]
	v_mfma_f32_16x16x32_bf16 v[68:71], v[158:161], v[228:231], v[68:71]
	v_mfma_f32_16x16x32_bf16 v[64:67], v[196:199], v[228:231], v[64:67]
	v_mfma_f32_16x16x32_bf16 v[116:119], v[188:191], v[208:211], v[116:119]
	v_mfma_f32_16x16x32_bf16 v[112:115], v[200:203], v[208:211], v[112:115]
	v_mfma_f32_16x16x32_bf16 v[100:103], v[188:191], v[216:219], v[100:103]
	v_mfma_f32_16x16x32_bf16 v[96:99], v[200:203], v[216:219], v[96:99]
	v_mfma_f32_16x16x32_bf16 v[84:87], v[188:191], v[224:227], v[84:87]
	v_mfma_f32_16x16x32_bf16 v[80:83], v[200:203], v[224:227], v[80:83]
	v_mfma_f32_16x16x32_bf16 v[68:71], v[188:191], v[232:235], v[68:71]
	v_mfma_f32_16x16x32_bf16 v[64:67], v[200:203], v[232:235], v[64:67]
	s_setprio 0
	s_barrier
; #define PG8_STAGE(bufoff, gbase, voff) do { _Pragma("unroll") for (int _i = 0; _i < 2; ++_i) \
;         __builtin_amdgcn_global_load_lds((const unsigned*)((const char*)(gbase) + (voff)[_i]), (PG8_LAS unsigned*)(lds + (bufoff) + ldsw + _i * 8192), 16, 0, 0); } while (0)
; #define PG8_LDA(dst, b, h) do { _Pragma("unroll") for (int m = 0; m < 4; ++m) _Pragma("unroll") for (int k = 0; k < 2; ++k) dst[m][k] = *(const PG8_LAS bf16x8*)(lds + PG8_SA(b, h) + aoff + m * 2048 + k * 1024); } while (0)
; #define PG8_MMA(ai, bj, At, Bt) do { __builtin_amdgcn_s_setprio(1); _Pragma("unroll") for (int m = 0; m < 4; ++m) _Pragma("unroll") for (int n = 0; n < 2; ++n) _Pragma("unroll") for (int k = 0; k < 2; ++k) \
;         acc[ai][bj][m][n] = __builtin_amdgcn_mfma_f32_16x16x32_bf16(Bt[n][k], At[m][k], acc[ai][bj][m][n], 0, 0, 0); __builtin_amdgcn_s_setprio(0); } while (0)
; #define PG8_WAIT_V(n) asm volatile("s_waitcnt vmcnt(" #n ")" ::: "memory")
; #define PG8_WAIT_L(n) asm volatile("s_waitcnt lgkmcnt(" #n ")" ::: "memory")
; #define PG8_BAR __builtin_amdgcn_s_barrier()
; #define PG8_SCHED __builtin_amdgcn_sched_barrier(0)
; template <class Epi, class Sched, bool ALIGN_EPI = false, bool SP2 = false>
; __device__ __forceinline__ void gemm_phase(PG8_LAS unsigned char* lds, const Gemm g, const Sched& S, const Epi& E, const int tid) {
;     ...
;             PG8_LDA(At, 1, 1); PG8_STAGE(PG8_SB(1, 0), b3, voffB); PG8_STAGE(PG8_SB(1, 1), b3 + hstep, voffB); PG8_STAGE(PG8_SA(1, 0), a3, voffA);
;             PG8_WAIT_V(8); PG8_WAIT_L(0); PG8_BAR; PG8_MMA(1, 0, At, B0); PG8_MMA(1, 1, At, B1); PG8_BAR; PG8_SCHED;
;     ...
;         if constexpr (ALIGN_EPI) { if (wr == 0) PG8_BAR; }
	s_add_i32 s9, s9, s95
	v_lshl_add_u64 v[162:163], v[162:163], 0, s[22:23]
	s_mov_b32 m0, s9
	ds_read_b128 v[204:207], v170 offset:49152
	ds_read_b128 v[208:211], v170 offset:50176
	ds_read_b128 v[212:215], v170 offset:51200
	ds_read_b128 v[216:219], v170 offset:52224
	ds_read_b128 v[220:223], v170 offset:53248
	ds_read_b128 v[224:227], v170 offset:54272
	ds_read_b128 v[228:231], v170 offset:55296
	ds_read_b128 v[232:235], v170 offset:56320
	global_load_lds_dwordx4 v[162:163], off
	s_add_i32 m0, s9, 0x2000
	s_add_u32 s42, s42, 0x40080
	v_lshl_add_u64 v[162:163], v[236:237], 0, s[22:23]
	s_addc_u32 s43, s43, 0
	s_add_i32 s9, s10, s95
	global_load_lds_dwordx4 v[162:163], off
	v_lshl_add_u64 v[162:163], s[42:43], 0, v[130:131]
	s_mov_b32 m0, s9
	s_nop 0
	global_load_lds_dwordx4 v[162:163], off
	v_lshl_add_u64 v[162:163], s[42:43], 0, v[134:135]
	s_add_i32 m0, s9, 0x2000
	s_nop 0
	global_load_lds_dwordx4 v[162:163], off
	v_lshl_add_u64 v[162:163], v[238:239], 0, s[22:23]
	s_mov_b32 m0, s5
	s_nop 0
	global_load_lds_dwordx4 v[162:163], off
	v_lshl_add_u64 v[162:163], v[240:241], 0, s[22:23]
	s_mov_b32 m0, s6
	s_nop 0
	global_load_lds_dwordx4 v[162:163], off
	s_waitcnt vmcnt(8)
	s_waitcnt lgkmcnt(0)
	s_barrier
	s_setprio 1
	s_waitcnt lgkmcnt(0)
	v_mfma_f32_16x16x32_bf16 v[60:63], v[142:145], v[204:207], v[60:63]
	v_mfma_f32_16x16x32_bf16 v[56:59], v[150:153], v[204:207], v[56:59]
	v_mfma_f32_16x16x32_bf16 v[44:47], v[142:145], v[212:215], v[44:47]
	v_mfma_f32_16x16x32_bf16 v[40:43], v[150:153], v[212:215], v[40:43]
	v_mfma_f32_16x16x32_bf16 v[28:31], v[142:145], v[220:223], v[28:31]
	v_mfma_f32_16x16x32_bf16 v[24:27], v[150:153], v[220:223], v[24:27]
	v_mfma_f32_16x16x32_bf16 v[12:15], v[142:145], v[228:231], v[12:15]
	v_mfma_f32_16x16x32_bf16 v[8:11], v[150:153], v[228:231], v[8:11]
	v_mfma_f32_16x16x32_bf16 v[60:63], v[146:149], v[208:211], v[60:63]
	v_mfma_f32_16x16x32_bf16 v[56:59], v[154:157], v[208:211], v[56:59]
	v_mfma_f32_16x16x32_bf16 v[44:47], v[146:149], v[216:219], v[44:47]
	v_mfma_f32_16x16x32_bf16 v[40:43], v[154:157], v[216:219], v[40:43]
	v_mfma_f32_16x16x32_bf16 v[28:31], v[146:149], v[224:227], v[28:31]
	v_mfma_f32_16x16x32_bf16 v[24:27], v[154:157], v[224:227], v[24:27]
	v_mfma_f32_16x16x32_bf16 v[12:15], v[146:149], v[232:235], v[12:15]
	v_mfma_f32_16x16x32_bf16 v[8:11], v[154:157], v[232:235], v[8:11]
	v_mfma_f32_16x16x32_bf16 v[52:55], v[158:161], v[204:207], v[52:55]
	v_mfma_f32_16x16x32_bf16 v[48:51], v[196:199], v[204:207], v[48:51]
	v_mfma_f32_16x16x32_bf16 v[36:39], v[158:161], v[212:215], v[36:39]
	v_mfma_f32_16x16x32_bf16 v[32:35], v[196:199], v[212:215], v[32:35]
	v_mfma_f32_16x16x32_bf16 v[20:23], v[158:161], v[220:223], v[20:23]
	v_mfma_f32_16x16x32_bf16 v[16:19], v[196:199], v[220:223], v[16:19]
	v_mfma_f32_16x16x32_bf16 v[4:7], v[158:161], v[228:231], v[4:7]
	v_mfma_f32_16x16x32_bf16 v[0:3], v[196:199], v[228:231], v[0:3]
	v_mfma_f32_16x16x32_bf16 v[52:55], v[188:191], v[208:211], v[52:55]
	v_mfma_f32_16x16x32_bf16 v[48:51], v[200:203], v[208:211], v[48:51]
	v_mfma_f32_16x16x32_bf16 v[36:39], v[188:191], v[216:219], v[36:39]
	v_mfma_f32_16x16x32_bf16 v[32:35], v[200:203], v[216:219], v[32:35]
	v_mfma_f32_16x16x32_bf16 v[20:23], v[188:191], v[224:227], v[20:23]
	v_mfma_f32_16x16x32_bf16 v[16:19], v[200:203], v[224:227], v[16:19]
	v_mfma_f32_16x16x32_bf16 v[4:7], v[188:191], v[232:235], v[4:7]
	v_mfma_f32_16x16x32_bf16 v[0:3], v[200:203], v[232:235], v[0:3]
	s_setprio 0
	s_barrier
	s_add_i32 s8, s8, 2
	s_add_u32 s0, s0, 0x100
	s_addc_u32 s1, s1, 0
	s_add_u32 s56, s56, 0x100
	s_addc_u32 s57, s57, 0
	s_cmp_gt_u32 s8, 13
	s_cbranch_scc0 .LBB0_459
	s_and_b64 vcc, exec, s[66:67]
	s_cbranch_vccz .LBB0_462
	s_barrier
